# LN epilogue entry: K-loop drain (vmcnt+barrier) moved below the hoisted residual loads as vmcnt(24)
# baseline (speedup 1.0000x reference)
.LBB0_438:
	s_lshl_b32 s2, s14, 5
	s_lshl_b32 s3, s0, 8
	s_or_b32 s2, s3, s2
	v_lshrrev_b32_e32 v0, 2, v148
	s_lshl_b32 s6, s87, 8
	v_and_or_b32 v164, v0, 12, s2
	s_add_i32 s2, s6, s96
	v_or_b32_e32 v0, s2, v176
	v_readlane_b32 s2, v253, 15
	v_lshl_add_u32 v2, v0, 10, v164
	v_readlane_b32 s3, v253, 16
	v_mov_b32_e32 v134, v3
	v_lshl_add_u64 v[0:1], v[2:3], 1, s[2:3]
	global_load_dwordx2 v[132:133], v[0:1], off
	global_load_dwordx2 v[136:137], v[0:1], off offset:32
	global_load_dwordx2 v[140:141], v[0:1], off offset:256
	global_load_dwordx2 v[144:145], v[0:1], off offset:288
	v_add_u32_e32 v0, 0x4000, v2
	v_mov_b32_e32 v1, v3
	v_lshl_add_u64 v[0:1], v[0:1], 1, s[2:3]
	global_load_dwordx2 v[150:151], v[0:1], off
	global_load_dwordx2 v[178:179], v[0:1], off offset:32
	global_load_dwordx2 v[182:183], v[0:1], off offset:256
	global_load_dwordx2 v[186:187], v[0:1], off offset:288
	v_mov_b32_e32 v135, v3
	v_mov_b32_e32 v138, v3
	v_mov_b32_e32 v139, v3
	v_mov_b32_e32 v142, v3
	v_mov_b32_e32 v143, v3
	v_mov_b32_e32 v146, v3
	v_mov_b32_e32 v147, v3
	v_mov_b32_e32 v152, v3
	v_mov_b32_e32 v153, v3
	v_mov_b32_e32 v180, v3
	v_mov_b32_e32 v181, v3
	v_mov_b32_e32 v184, v3
	v_mov_b32_e32 v185, v3
	v_mov_b32_e32 v188, v3
	v_mov_b32_e32 v189, v3
	v_and_b32_e32 v149, 63, v148
	v_add_u32_e32 v0, 0x8000, v2
	v_mov_b32_e32 v1, v3
	v_lshl_add_u64 v[0:1], v[0:1], 1, s[2:3]
	global_load_dwordx2 v[200:201], v[0:1], off
	global_load_dwordx2 v[202:203], v[0:1], off offset:32
	global_load_dwordx2 v[204:205], v[0:1], off offset:256
	global_load_dwordx2 v[206:207], v[0:1], off offset:288
	v_add_u32_e32 v0, 0xc000, v2
	v_mov_b32_e32 v1, v3
	v_lshl_add_u64 v[0:1], v[0:1], 1, s[2:3]
	global_load_dwordx2 v[208:209], v[0:1], off
	global_load_dwordx2 v[210:211], v[0:1], off offset:32
	global_load_dwordx2 v[212:213], v[0:1], off offset:256
	global_load_dwordx2 v[214:215], v[0:1], off offset:288
	v_add_u32_e32 v0, 0x20000, v2
	v_mov_b32_e32 v1, v3
	v_lshl_add_u64 v[0:1], v[0:1], 1, s[2:3]
	global_load_dwordx2 v[222:223], v[0:1], off
	global_load_dwordx2 v[220:221], v[0:1], off offset:32
	global_load_dwordx2 v[218:219], v[0:1], off offset:256
	global_load_dwordx2 v[216:217], v[0:1], off offset:288
	v_add_u32_e32 v0, 0x24000, v2
	v_mov_b32_e32 v1, v3
	v_lshl_add_u64 v[0:1], v[0:1], 1, s[2:3]
	global_load_dwordx2 v[224:225], v[0:1], off
	global_load_dwordx2 v[226:227], v[0:1], off offset:32
	global_load_dwordx2 v[228:229], v[0:1], off offset:256
	global_load_dwordx2 v[230:231], v[0:1], off offset:288
	s_waitcnt vmcnt(24)
	s_barrier
	s_waitcnt vmcnt(16)
	s_nop 0
	v_cvt_f32_f16_e32 v0, v132
	v_cvt_f32_f16_sdwa v1, v132 dst_sel:DWORD dst_unused:UNUSED_PAD src0_sel:WORD_1
	v_cvt_f32_f16_e32 v132, v133
	v_cvt_f32_f16_sdwa v133, v133 dst_sel:DWORD dst_unused:UNUSED_PAD src0_sel:WORD_1
	v_mov_b32_e32 v134, v3
	v_pk_fma_f32 v[28:29], v[0:1], s[86:87], v[28:29] op_sel_hi:[1,0,1]
	v_cvt_f32_f16_e32 v0, v136
	v_pk_fma_f32 v[30:31], v[132:133], s[86:87], v[30:31] op_sel_hi:[1,0,1]
	v_cvt_f32_f16_sdwa v1, v136 dst_sel:DWORD dst_unused:UNUSED_PAD src0_sel:WORD_1
	v_cvt_f32_f16_e32 v132, v137
	v_cvt_f32_f16_sdwa v133, v137 dst_sel:DWORD dst_unused:UNUSED_PAD src0_sel:WORD_1
	v_mov_b32_e32 v135, v3
	v_pk_fma_f32 v[20:21], v[0:1], s[86:87], v[20:21] op_sel_hi:[1,0,1]
	v_cvt_f32_f16_e32 v0, v140
	v_pk_fma_f32 v[22:23], v[132:133], s[86:87], v[22:23] op_sel_hi:[1,0,1]
	v_cvt_f32_f16_sdwa v1, v140 dst_sel:DWORD dst_unused:UNUSED_PAD src0_sel:WORD_1
	v_cvt_f32_f16_e32 v132, v141
	v_cvt_f32_f16_sdwa v133, v141 dst_sel:DWORD dst_unused:UNUSED_PAD src0_sel:WORD_1
	v_mov_b32_e32 v138, v3
	v_pk_fma_f32 v[12:13], v[0:1], s[86:87], v[12:13] op_sel_hi:[1,0,1]
	v_cvt_f32_f16_e32 v0, v144
	v_pk_fma_f32 v[14:15], v[132:133], s[86:87], v[14:15] op_sel_hi:[1,0,1]
	v_cvt_f32_f16_sdwa v1, v144 dst_sel:DWORD dst_unused:UNUSED_PAD src0_sel:WORD_1
	v_cvt_f32_f16_e32 v132, v145
	v_cvt_f32_f16_sdwa v133, v145 dst_sel:DWORD dst_unused:UNUSED_PAD src0_sel:WORD_1
	v_mov_b32_e32 v139, v3
	v_pk_fma_f32 v[4:5], v[0:1], s[86:87], v[4:5] op_sel_hi:[1,0,1]
	v_cvt_f32_f16_e32 v0, v150
	v_pk_fma_f32 v[6:7], v[132:133], s[86:87], v[6:7] op_sel_hi:[1,0,1]
	v_cvt_f32_f16_sdwa v1, v150 dst_sel:DWORD dst_unused:UNUSED_PAD src0_sel:WORD_1
	v_cvt_f32_f16_e32 v132, v151
	v_cvt_f32_f16_sdwa v133, v151 dst_sel:DWORD dst_unused:UNUSED_PAD src0_sel:WORD_1
	v_pk_fma_f32 v[32:33], v[0:1], s[86:87], v[32:33] op_sel_hi:[1,0,1]
	v_cvt_f32_f16_e32 v0, v178
	v_pk_fma_f32 v[34:35], v[132:133], s[86:87], v[34:35] op_sel_hi:[1,0,1]
	v_cvt_f32_f16_sdwa v1, v178 dst_sel:DWORD dst_unused:UNUSED_PAD src0_sel:WORD_1
	v_cvt_f32_f16_e32 v132, v179
	v_cvt_f32_f16_sdwa v133, v179 dst_sel:DWORD dst_unused:UNUSED_PAD src0_sel:WORD_1
	v_mov_b32_e32 v142, v3
	v_pk_fma_f32 v[24:25], v[0:1], s[86:87], v[24:25] op_sel_hi:[1,0,1]
	v_cvt_f32_f16_e32 v0, v182
	v_pk_fma_f32 v[26:27], v[132:133], s[86:87], v[26:27] op_sel_hi:[1,0,1]
	v_cvt_f32_f16_sdwa v1, v182 dst_sel:DWORD dst_unused:UNUSED_PAD src0_sel:WORD_1
	v_cvt_f32_f16_e32 v132, v183
	v_cvt_f32_f16_sdwa v133, v183 dst_sel:DWORD dst_unused:UNUSED_PAD src0_sel:WORD_1
	v_mov_b32_e32 v143, v3
	v_pk_fma_f32 v[16:17], v[0:1], s[86:87], v[16:17] op_sel_hi:[1,0,1]
	v_cvt_f32_f16_e32 v0, v186
	v_pk_fma_f32 v[18:19], v[132:133], s[86:87], v[18:19] op_sel_hi:[1,0,1]
	v_cvt_f32_f16_sdwa v1, v186 dst_sel:DWORD dst_unused:UNUSED_PAD src0_sel:WORD_1
	v_cvt_f32_f16_e32 v132, v187
	v_cvt_f32_f16_sdwa v133, v187 dst_sel:DWORD dst_unused:UNUSED_PAD src0_sel:WORD_1
	v_mov_b32_e32 v146, v3
	v_pk_fma_f32 v[8:9], v[0:1], s[86:87], v[8:9] op_sel_hi:[1,0,1]
	v_pk_fma_f32 v[10:11], v[132:133], s[86:87], v[10:11] op_sel_hi:[1,0,1]
	v_mov_b32_e32 v147, v3
	v_mov_b32_e32 v152, v3
	v_mov_b32_e32 v153, v3
	v_mov_b32_e32 v180, v3
	v_mov_b32_e32 v181, v3
	v_mov_b32_e32 v184, v3
	v_mov_b32_e32 v185, v3
	v_mov_b32_e32 v188, v3
	v_mov_b32_e32 v189, v3
	s_waitcnt vmcnt(8)
	s_nop 0
	v_cvt_f32_f16_e32 v0, v200
	v_cvt_f32_f16_sdwa v1, v200 dst_sel:DWORD dst_unused:UNUSED_PAD src0_sel:WORD_1
	v_cvt_f32_f16_e32 v200, v201
	v_cvt_f32_f16_sdwa v201, v201 dst_sel:DWORD dst_unused:UNUSED_PAD src0_sel:WORD_1
	v_mov_b32_e32 v146, v3
	v_pk_fma_f32 v[60:61], v[0:1], s[86:87], v[60:61] op_sel_hi:[1,0,1]
	v_cvt_f32_f16_e32 v0, v202
	v_pk_fma_f32 v[62:63], v[200:201], s[86:87], v[62:63] op_sel_hi:[1,0,1]
	v_cvt_f32_f16_sdwa v1, v202 dst_sel:DWORD dst_unused:UNUSED_PAD src0_sel:WORD_1
	v_cvt_f32_f16_e32 v200, v203
	v_cvt_f32_f16_sdwa v201, v203 dst_sel:DWORD dst_unused:UNUSED_PAD src0_sel:WORD_1
	v_mov_b32_e32 v147, v3
	v_pk_fma_f32 v[52:53], v[0:1], s[86:87], v[52:53] op_sel_hi:[1,0,1]
	v_cvt_f32_f16_e32 v0, v204
	v_pk_fma_f32 v[54:55], v[200:201], s[86:87], v[54:55] op_sel_hi:[1,0,1]
	v_cvt_f32_f16_sdwa v1, v204 dst_sel:DWORD dst_unused:UNUSED_PAD src0_sel:WORD_1
	v_cvt_f32_f16_e32 v200, v205
	v_cvt_f32_f16_sdwa v201, v205 dst_sel:DWORD dst_unused:UNUSED_PAD src0_sel:WORD_1
	v_mov_b32_e32 v142, v3
	v_pk_fma_f32 v[44:45], v[0:1], s[86:87], v[44:45] op_sel_hi:[1,0,1]
	v_cvt_f32_f16_e32 v0, v206
	v_pk_fma_f32 v[46:47], v[200:201], s[86:87], v[46:47] op_sel_hi:[1,0,1]
	v_cvt_f32_f16_sdwa v1, v206 dst_sel:DWORD dst_unused:UNUSED_PAD src0_sel:WORD_1
	v_cvt_f32_f16_e32 v200, v207
	v_cvt_f32_f16_sdwa v201, v207 dst_sel:DWORD dst_unused:UNUSED_PAD src0_sel:WORD_1
	v_mov_b32_e32 v143, v3
	v_pk_fma_f32 v[36:37], v[0:1], s[86:87], v[36:37] op_sel_hi:[1,0,1]
	v_cvt_f32_f16_e32 v0, v208
	v_pk_fma_f32 v[38:39], v[200:201], s[86:87], v[38:39] op_sel_hi:[1,0,1]
	v_cvt_f32_f16_sdwa v1, v208 dst_sel:DWORD dst_unused:UNUSED_PAD src0_sel:WORD_1
	v_cvt_f32_f16_e32 v200, v209
	v_cvt_f32_f16_sdwa v201, v209 dst_sel:DWORD dst_unused:UNUSED_PAD src0_sel:WORD_1
	v_pk_fma_f32 v[64:65], v[0:1], s[86:87], v[64:65] op_sel_hi:[1,0,1]
	v_cvt_f32_f16_e32 v0, v210
	v_pk_fma_f32 v[66:67], v[200:201], s[86:87], v[66:67] op_sel_hi:[1,0,1]
	v_cvt_f32_f16_sdwa v1, v210 dst_sel:DWORD dst_unused:UNUSED_PAD src0_sel:WORD_1
	v_cvt_f32_f16_e32 v200, v211
	v_cvt_f32_f16_sdwa v201, v211 dst_sel:DWORD dst_unused:UNUSED_PAD src0_sel:WORD_1
	v_mov_b32_e32 v138, v3
	v_pk_fma_f32 v[56:57], v[0:1], s[86:87], v[56:57] op_sel_hi:[1,0,1]
	v_cvt_f32_f16_e32 v0, v212
	v_pk_fma_f32 v[58:59], v[200:201], s[86:87], v[58:59] op_sel_hi:[1,0,1]
	v_cvt_f32_f16_sdwa v1, v212 dst_sel:DWORD dst_unused:UNUSED_PAD src0_sel:WORD_1
	v_cvt_f32_f16_e32 v200, v213
	v_cvt_f32_f16_sdwa v201, v213 dst_sel:DWORD dst_unused:UNUSED_PAD src0_sel:WORD_1
	v_mov_b32_e32 v139, v3
	v_pk_fma_f32 v[48:49], v[0:1], s[86:87], v[48:49] op_sel_hi:[1,0,1]
	v_cvt_f32_f16_e32 v0, v214
	v_pk_fma_f32 v[50:51], v[200:201], s[86:87], v[50:51] op_sel_hi:[1,0,1]
	v_cvt_f32_f16_sdwa v1, v214 dst_sel:DWORD dst_unused:UNUSED_PAD src0_sel:WORD_1
	v_cvt_f32_f16_e32 v200, v215
	v_cvt_f32_f16_sdwa v201, v215 dst_sel:DWORD dst_unused:UNUSED_PAD src0_sel:WORD_1
	v_mov_b32_e32 v134, v3
	v_pk_fma_f32 v[40:41], v[0:1], s[86:87], v[40:41] op_sel_hi:[1,0,1]
	v_pk_fma_f32 v[42:43], v[200:201], s[86:87], v[42:43] op_sel_hi:[1,0,1]
	v_mov_b32_e32 v135, v3
	v_mov_b32_e32 v152, v3
	v_mov_b32_e32 v153, v3
	v_mov_b32_e32 v180, v3
	v_mov_b32_e32 v181, v3
	v_mov_b32_e32 v184, v3
	v_mov_b32_e32 v185, v3
	v_mov_b32_e32 v188, v3
	v_mov_b32_e32 v189, v3
	s_waitcnt vmcnt(0)
	s_nop 0
	v_cvt_f32_f16_e32 v0, v222
	v_cvt_f32_f16_sdwa v1, v222 dst_sel:DWORD dst_unused:UNUSED_PAD src0_sel:WORD_1
	v_cvt_f32_f16_e32 v134, v223
	v_cvt_f32_f16_sdwa v135, v223 dst_sel:DWORD dst_unused:UNUSED_PAD src0_sel:WORD_1
	v_mov_b32_e32 v142, v3
	v_pk_fma_f32 v[92:93], v[0:1], s[86:87], v[92:93] op_sel_hi:[1,0,1]
	v_cvt_f32_f16_e32 v0, v220
	v_cvt_f32_f16_sdwa v1, v220 dst_sel:DWORD dst_unused:UNUSED_PAD src0_sel:WORD_1
	v_pk_fma_f32 v[94:95], v[134:135], s[86:87], v[94:95] op_sel_hi:[1,0,1]
	v_cvt_f32_f16_e32 v134, v221
	v_cvt_f32_f16_sdwa v135, v221 dst_sel:DWORD dst_unused:UNUSED_PAD src0_sel:WORD_1
	v_pk_fma_f32 v[84:85], v[0:1], s[86:87], v[84:85] op_sel_hi:[1,0,1]
	v_cvt_f32_f16_e32 v0, v218
	v_cvt_f32_f16_sdwa v1, v218 dst_sel:DWORD dst_unused:UNUSED_PAD src0_sel:WORD_1
	v_pk_fma_f32 v[86:87], v[134:135], s[86:87], v[86:87] op_sel_hi:[1,0,1]
	v_cvt_f32_f16_e32 v134, v219
	v_cvt_f32_f16_sdwa v135, v219 dst_sel:DWORD dst_unused:UNUSED_PAD src0_sel:WORD_1
	v_pk_fma_f32 v[76:77], v[0:1], s[86:87], v[76:77] op_sel_hi:[1,0,1]
	v_cvt_f32_f16_e32 v0, v216
	v_cvt_f32_f16_sdwa v1, v216 dst_sel:DWORD dst_unused:UNUSED_PAD src0_sel:WORD_1
	v_cvt_f32_f16_e32 v216, v217
	v_cvt_f32_f16_sdwa v217, v217 dst_sel:DWORD dst_unused:UNUSED_PAD src0_sel:WORD_1
	v_pk_fma_f32 v[78:79], v[134:135], s[86:87], v[78:79] op_sel_hi:[1,0,1]
	v_pk_fma_f32 v[68:69], v[0:1], s[86:87], v[68:69] op_sel_hi:[1,0,1]
	v_cvt_f32_f16_e32 v0, v224
	v_pk_fma_f32 v[70:71], v[216:217], s[86:87], v[70:71] op_sel_hi:[1,0,1]
	v_cvt_f32_f16_sdwa v1, v224 dst_sel:DWORD dst_unused:UNUSED_PAD src0_sel:WORD_1
	v_cvt_f32_f16_e32 v216, v225
	v_cvt_f32_f16_sdwa v217, v225 dst_sel:DWORD dst_unused:UNUSED_PAD src0_sel:WORD_1
	v_pk_fma_f32 v[96:97], v[0:1], s[86:87], v[96:97] op_sel_hi:[1,0,1]
	v_cvt_f32_f16_e32 v0, v226
	v_pk_fma_f32 v[98:99], v[216:217], s[86:87], v[98:99] op_sel_hi:[1,0,1]
	v_cvt_f32_f16_sdwa v1, v226 dst_sel:DWORD dst_unused:UNUSED_PAD src0_sel:WORD_1
	v_cvt_f32_f16_e32 v216, v227
	v_cvt_f32_f16_sdwa v217, v227 dst_sel:DWORD dst_unused:UNUSED_PAD src0_sel:WORD_1
	v_mov_b32_e32 v143, v3
	v_pk_fma_f32 v[88:89], v[0:1], s[86:87], v[88:89] op_sel_hi:[1,0,1]
	v_cvt_f32_f16_e32 v0, v228
	v_pk_fma_f32 v[90:91], v[216:217], s[86:87], v[90:91] op_sel_hi:[1,0,1]
	v_cvt_f32_f16_sdwa v1, v228 dst_sel:DWORD dst_unused:UNUSED_PAD src0_sel:WORD_1
	v_cvt_f32_f16_e32 v216, v229
	v_cvt_f32_f16_sdwa v217, v229 dst_sel:DWORD dst_unused:UNUSED_PAD src0_sel:WORD_1
	v_mov_b32_e32 v138, v3
	v_pk_fma_f32 v[80:81], v[0:1], s[86:87], v[80:81] op_sel_hi:[1,0,1]
	v_cvt_f32_f16_e32 v0, v230
	v_pk_fma_f32 v[82:83], v[216:217], s[86:87], v[82:83] op_sel_hi:[1,0,1]
	v_cvt_f32_f16_sdwa v1, v230 dst_sel:DWORD dst_unused:UNUSED_PAD src0_sel:WORD_1
	v_cvt_f32_f16_e32 v216, v231
	v_cvt_f32_f16_sdwa v217, v231 dst_sel:DWORD dst_unused:UNUSED_PAD src0_sel:WORD_1
	v_mov_b32_e32 v139, v3
	v_pk_fma_f32 v[72:73], v[0:1], s[86:87], v[72:73] op_sel_hi:[1,0,1]
	v_add_u32_e32 v0, 0x28000, v2
	v_pk_fma_f32 v[74:75], v[216:217], s[86:87], v[74:75] op_sel_hi:[1,0,1]
	v_mov_b32_e32 v1, v3
	v_add_u32_e32 v2, 0x2c000, v2
	v_lshl_add_u64 v[132:133], v[0:1], 1, s[2:3]
	v_lshl_add_u64 v[134:135], v[2:3], 1, s[2:3]
	global_load_dwordx2 v[0:1], v[132:133], off
	global_load_dwordx2 v[140:141], v[132:133], off offset:32
	global_load_dwordx2 v[136:137], v[132:133], off offset:256
	s_nop 0
	global_load_dwordx2 v[132:133], v[132:133], off offset:288
	s_nop 0
	global_load_dwordx2 v[144:145], v[134:135], off
	global_load_dwordx2 v[150:151], v[134:135], off offset:32
	global_load_dwordx2 v[178:179], v[134:135], off offset:256
	global_load_dwordx2 v[182:183], v[134:135], off offset:288
	v_mov_b32_e32 v2, v3
	v_mov_b32_e32 v134, v3
	v_mov_b32_e32 v135, v3
	v_mov_b32_e32 v146, v3
	v_mov_b32_e32 v147, v3
	v_mov_b32_e32 v152, v3
	v_mov_b32_e32 v153, v3
	v_mov_b32_e32 v180, v3
	v_mov_b32_e32 v181, v3
	v_mov_b32_e32 v184, v3
	v_mov_b32_e32 v185, v3
	s_lshl_b32 s2, s14, 3
	s_add_i32 s7, s2, 0
	s_waitcnt vmcnt(7)
	v_mov_b64_e32 v[188:189], v[2:3]
	v_mov_b64_e32 v[186:187], v[0:1]
	s_waitcnt vmcnt(0)
	s_nop 0
	v_cvt_f32_f16_e32 v0, v186
	v_cvt_f32_f16_sdwa v1, v186 dst_sel:DWORD dst_unused:UNUSED_PAD src0_sel:WORD_1
	v_cvt_f32_f16_e32 v134, v187
	v_cvt_f32_f16_sdwa v135, v187 dst_sel:DWORD dst_unused:UNUSED_PAD src0_sel:WORD_1
	v_xor_b32_e32 v2, 32, v171
	v_pk_fma_f32 v[124:125], v[0:1], s[86:87], v[124:125] op_sel_hi:[1,0,1]
	v_cvt_f32_f16_e32 v0, v140
	v_cvt_f32_f16_sdwa v1, v140 dst_sel:DWORD dst_unused:UNUSED_PAD src0_sel:WORD_1
	v_pk_fma_f32 v[126:127], v[134:135], s[86:87], v[126:127] op_sel_hi:[1,0,1]
	v_cvt_f32_f16_e32 v134, v141
	v_cvt_f32_f16_sdwa v135, v141 dst_sel:DWORD dst_unused:UNUSED_PAD src0_sel:WORD_1
	v_pk_fma_f32 v[116:117], v[0:1], s[86:87], v[116:117] op_sel_hi:[1,0,1]
	v_cvt_f32_f16_e32 v0, v136
	v_cvt_f32_f16_sdwa v1, v136 dst_sel:DWORD dst_unused:UNUSED_PAD src0_sel:WORD_1
	v_pk_fma_f32 v[118:119], v[134:135], s[86:87], v[118:119] op_sel_hi:[1,0,1]
	v_cvt_f32_f16_e32 v134, v137
	v_cvt_f32_f16_sdwa v135, v137 dst_sel:DWORD dst_unused:UNUSED_PAD src0_sel:WORD_1
	v_pk_fma_f32 v[108:109], v[0:1], s[86:87], v[108:109] op_sel_hi:[1,0,1]
	v_cvt_f32_f16_e32 v0, v132
	v_cvt_f32_f16_sdwa v1, v132 dst_sel:DWORD dst_unused:UNUSED_PAD src0_sel:WORD_1
	v_cvt_f32_f16_e32 v132, v133
	v_cvt_f32_f16_sdwa v133, v133 dst_sel:DWORD dst_unused:UNUSED_PAD src0_sel:WORD_1
	v_pk_fma_f32 v[110:111], v[134:135], s[86:87], v[110:111] op_sel_hi:[1,0,1]
	v_pk_fma_f32 v[100:101], v[0:1], s[86:87], v[100:101] op_sel_hi:[1,0,1]
	v_cvt_f32_f16_e32 v0, v144
	v_cvt_f32_f16_sdwa v1, v144 dst_sel:DWORD dst_unused:UNUSED_PAD src0_sel:WORD_1
	v_pk_fma_f32 v[102:103], v[132:133], s[86:87], v[102:103] op_sel_hi:[1,0,1]
	v_cvt_f32_f16_e32 v132, v145
	v_cvt_f32_f16_sdwa v133, v145 dst_sel:DWORD dst_unused:UNUSED_PAD src0_sel:WORD_1
	v_pk_fma_f32 v[128:129], v[0:1], s[86:87], v[128:129] op_sel_hi:[1,0,1]
	v_cvt_f32_f16_e32 v0, v150
	v_cvt_f32_f16_sdwa v1, v150 dst_sel:DWORD dst_unused:UNUSED_PAD src0_sel:WORD_1
	v_pk_fma_f32 v[130:131], v[132:133], s[86:87], v[130:131] op_sel_hi:[1,0,1]
	v_cvt_f32_f16_e32 v132, v151
	v_cvt_f32_f16_sdwa v133, v151 dst_sel:DWORD dst_unused:UNUSED_PAD src0_sel:WORD_1
	v_pk_fma_f32 v[120:121], v[0:1], s[86:87], v[120:121] op_sel_hi:[1,0,1]
	v_cvt_f32_f16_e32 v0, v178
	v_cvt_f32_f16_sdwa v1, v178 dst_sel:DWORD dst_unused:UNUSED_PAD src0_sel:WORD_1
	v_pk_fma_f32 v[122:123], v[132:133], s[86:87], v[122:123] op_sel_hi:[1,0,1]
	v_cvt_f32_f16_e32 v132, v179
	v_cvt_f32_f16_sdwa v133, v179 dst_sel:DWORD dst_unused:UNUSED_PAD src0_sel:WORD_1
	v_pk_fma_f32 v[112:113], v[0:1], s[86:87], v[112:113] op_sel_hi:[1,0,1]
	v_cvt_f32_f16_e32 v0, v182
	v_cvt_f32_f16_sdwa v1, v182 dst_sel:DWORD dst_unused:UNUSED_PAD src0_sel:WORD_1
	v_pk_fma_f32 v[114:115], v[132:133], s[86:87], v[114:115] op_sel_hi:[1,0,1]
	v_cvt_f32_f16_e32 v132, v183
	v_cvt_f32_f16_sdwa v133, v183 dst_sel:DWORD dst_unused:UNUSED_PAD src0_sel:WORD_1
	v_pk_fma_f32 v[104:105], v[0:1], s[86:87], v[104:105] op_sel_hi:[1,0,1]
	v_and_b32_e32 v1, 64, v171
	v_xor_b32_e32 v0, 16, v171
	v_pk_fma_f32 v[106:107], v[132:133], s[86:87], v[106:107] op_sel_hi:[1,0,1]
	v_add_u32_e32 v1, 64, v1
	v_mov_b32_e32 v132, v29
	v_mov_b32_e32 v133, v30
	v_mov_b32_e32 v134, v28
	v_mov_b32_e32 v135, v31
	v_cmp_lt_i32_e32 vcc, v0, v1
	v_pk_add_f32 v[132:133], v[132:133], v[134:135]
	v_mov_b32_e32 v134, v21
	v_mov_b32_e32 v135, v22
	v_mov_b32_e32 v136, v20
	v_mov_b32_e32 v137, v23
	v_cndmask_b32_e32 v0, v171, v0, vcc
	v_cmp_lt_i32_e32 vcc, v2, v1
	v_pk_add_f32 v[134:135], v[134:135], v[136:137]
	v_add_f32_e32 v137, v12, v13
	v_cndmask_b32_e32 v1, v171, v2, vcc
	v_add_f32_e32 v2, v132, v133
	v_pk_add_f32 v[134:135], v[134:135], v[134:135] op_sel_hi:[0,1]
	v_add_f32_e32 v133, 0, v2
	v_add_f32_e32 v139, v14, v15
	v_mov_b32_e32 v136, v4
	v_mov_b32_e32 v138, v5
	v_mov_b32_e32 v134, v6
	v_mov_b32_e32 v132, v7
	v_pk_add_f32 v[136:137], v[136:137], v[138:139]
	v_pk_add_f32 v[132:133], v[134:135], v[132:133]
	v_lshlrev_b32_e32 v0, 2, v0
	v_pk_add_f32 v[132:133], v[136:137], v[132:133]
	v_lshlrev_b32_e32 v1, 2, v1
	v_add_f32_e32 v2, v132, v133
	v_mov_b32_e32 v132, v2
	s_nop 1
	v_permlane16_swap_b32 v2, v132
	v_cmp_gt_u32_e32 vcc, 16, v149
	s_waitcnt lgkmcnt(0)
	v_add_f32_e32 v2, v2, v132
	v_mov_b32_e32 v132, v2
	s_nop 1
	v_permlane32_swap_b32 v2, v132
	s_waitcnt lgkmcnt(0)
	v_add_f32_e32 v2, v2, v132
	v_fmamk_f32 v133, v2, 0xbc800000, v31
	v_fmamk_f32 v135, v2, 0xbc800000, v29
	v_fmamk_f32 v132, v2, 0xbc800000, v30
	v_fmamk_f32 v134, v2, 0xbc800000, v28
	v_mul_f32_e32 v135, v135, v135
	v_mul_f32_e32 v133, v133, v133
	v_fmac_f32_e32 v135, v134, v134
	v_fmac_f32_e32 v133, v132, v132
	v_fmamk_f32 v134, v2, 0xbc800000, v23
	v_fmamk_f32 v136, v2, 0xbc800000, v21
	v_add_f32_e32 v132, v135, v133
	v_fmamk_f32 v133, v2, 0xbc800000, v22
	v_fmamk_f32 v135, v2, 0xbc800000, v20
	v_mul_f32_e32 v136, v136, v136
	v_mul_f32_e32 v134, v134, v134
	v_fmac_f32_e32 v136, v135, v135
	v_fmac_f32_e32 v134, v133, v133
	v_add_f32_e32 v133, v136, v134
	v_fmamk_f32 v134, v2, 0xbc800000, v15
	v_fmamk_f32 v136, v2, 0xbc800000, v13
	v_add_f32_e32 v132, v132, v133
	v_fmamk_f32 v133, v2, 0xbc800000, v14
	v_fmamk_f32 v135, v2, 0xbc800000, v12
	v_mul_f32_e32 v136, v136, v136
	v_mul_f32_e32 v134, v134, v134
	v_fmac_f32_e32 v136, v135, v135
	v_fmac_f32_e32 v134, v133, v133
	v_add_f32_e32 v133, v136, v134
	v_fmamk_f32 v134, v2, 0xbc800000, v7
	v_fmamk_f32 v136, v2, 0xbc800000, v5
	v_add_f32_e32 v132, v133, v132
	v_fmamk_f32 v133, v2, 0xbc800000, v6
	v_fmamk_f32 v135, v2, 0xbc800000, v4
	v_mul_f32_e32 v136, v136, v136
	v_mul_f32_e32 v134, v134, v134
	v_fmac_f32_e32 v136, v135, v135
	v_fmac_f32_e32 v134, v133, v133
	v_add_f32_e32 v133, v136, v134
	v_add_f32_e32 v132, v133, v132
	v_mov_b32_e32 v133, v132
	s_nop 1
	v_permlane16_swap_b32 v132, v133
	s_waitcnt lgkmcnt(0)
	v_add_f32_e32 v132, v132, v133
	ds_bpermute_b32 v133, v1, v132
	s_and_saveexec_b64 s[4:5], vcc
	s_cbranch_execz .LBB0_440
	s_lshl_b32 s2, s80, 11
	s_add_i32 s2, s7, s2
	v_mul_f32_e32 v134, 0x3c800000, v2
	s_waitcnt lgkmcnt(0)
	v_add_f32_e32 v135, v132, v133
	v_lshl_add_u32 v2, v176, 5, s2
	ds_write_b64 v2, v[134:135]

.LBB0_506:
	s_lshl_b32 s2, s14, 5
	s_lshl_b32 s3, s0, 8
	s_or_b32 s2, s3, s2
	v_lshrrev_b32_e32 v0, 2, v148
	s_lshl_b32 s6, s87, 8
	v_and_or_b32 v164, v0, 12, s2
	s_add_i32 s2, s6, s94
	v_or_b32_e32 v0, s2, v176
	v_readlane_b32 s2, v253, 15
	v_lshl_add_u32 v2, v0, 10, v164
	v_readlane_b32 s3, v253, 16
	v_mov_b32_e32 v134, v3
	v_lshl_add_u64 v[0:1], v[2:3], 1, s[2:3]
	global_load_dwordx2 v[132:133], v[0:1], off
	global_load_dwordx2 v[136:137], v[0:1], off offset:32
	global_load_dwordx2 v[140:141], v[0:1], off offset:256
	global_load_dwordx2 v[144:145], v[0:1], off offset:288
	v_add_u32_e32 v0, 0x4000, v2
	v_mov_b32_e32 v1, v3
	v_lshl_add_u64 v[0:1], v[0:1], 1, s[2:3]
	global_load_dwordx2 v[150:151], v[0:1], off
	global_load_dwordx2 v[178:179], v[0:1], off offset:32
	global_load_dwordx2 v[182:183], v[0:1], off offset:256
	global_load_dwordx2 v[186:187], v[0:1], off offset:288
	v_mov_b32_e32 v135, v3
	v_mov_b32_e32 v138, v3
	v_mov_b32_e32 v139, v3
	v_mov_b32_e32 v142, v3
	v_mov_b32_e32 v143, v3
	v_mov_b32_e32 v146, v3
	v_mov_b32_e32 v147, v3
	v_mov_b32_e32 v152, v3
	v_mov_b32_e32 v153, v3
	v_mov_b32_e32 v180, v3
	v_mov_b32_e32 v181, v3
	v_mov_b32_e32 v184, v3
	v_mov_b32_e32 v185, v3
	v_mov_b32_e32 v188, v3
	v_mov_b32_e32 v189, v3
	v_and_b32_e32 v149, 63, v148
	v_add_u32_e32 v0, 0x8000, v2
	v_mov_b32_e32 v1, v3
	v_lshl_add_u64 v[0:1], v[0:1], 1, s[2:3]
	global_load_dwordx2 v[200:201], v[0:1], off
	global_load_dwordx2 v[202:203], v[0:1], off offset:32
	global_load_dwordx2 v[204:205], v[0:1], off offset:256
	global_load_dwordx2 v[206:207], v[0:1], off offset:288
	v_add_u32_e32 v0, 0xc000, v2
	v_mov_b32_e32 v1, v3
	v_lshl_add_u64 v[0:1], v[0:1], 1, s[2:3]
	global_load_dwordx2 v[208:209], v[0:1], off
	global_load_dwordx2 v[210:211], v[0:1], off offset:32
	global_load_dwordx2 v[212:213], v[0:1], off offset:256
	global_load_dwordx2 v[214:215], v[0:1], off offset:288
	v_add_u32_e32 v0, 0x20000, v2
	v_mov_b32_e32 v1, v3
	v_lshl_add_u64 v[0:1], v[0:1], 1, s[2:3]
	global_load_dwordx2 v[222:223], v[0:1], off
	global_load_dwordx2 v[220:221], v[0:1], off offset:32
	global_load_dwordx2 v[218:219], v[0:1], off offset:256
	global_load_dwordx2 v[216:217], v[0:1], off offset:288
	v_add_u32_e32 v0, 0x24000, v2
	v_mov_b32_e32 v1, v3
	v_lshl_add_u64 v[0:1], v[0:1], 1, s[2:3]
	global_load_dwordx2 v[224:225], v[0:1], off
	global_load_dwordx2 v[226:227], v[0:1], off offset:32
	global_load_dwordx2 v[228:229], v[0:1], off offset:256
	global_load_dwordx2 v[230:231], v[0:1], off offset:288
	s_waitcnt vmcnt(24)
	s_barrier
	s_waitcnt vmcnt(16)
	s_nop 0
	v_cvt_f32_f16_e32 v0, v132
	v_cvt_f32_f16_sdwa v1, v132 dst_sel:DWORD dst_unused:UNUSED_PAD src0_sel:WORD_1
	v_cvt_f32_f16_e32 v132, v133
	v_cvt_f32_f16_sdwa v133, v133 dst_sel:DWORD dst_unused:UNUSED_PAD src0_sel:WORD_1
	v_mov_b32_e32 v134, v3
	v_pk_fma_f32 v[28:29], v[0:1], s[86:87], v[28:29] op_sel_hi:[1,0,1]
	v_cvt_f32_f16_e32 v0, v136
	v_pk_fma_f32 v[30:31], v[132:133], s[86:87], v[30:31] op_sel_hi:[1,0,1]
	v_cvt_f32_f16_sdwa v1, v136 dst_sel:DWORD dst_unused:UNUSED_PAD src0_sel:WORD_1
	v_cvt_f32_f16_e32 v132, v137
	v_cvt_f32_f16_sdwa v133, v137 dst_sel:DWORD dst_unused:UNUSED_PAD src0_sel:WORD_1
	v_mov_b32_e32 v135, v3
	v_pk_fma_f32 v[20:21], v[0:1], s[86:87], v[20:21] op_sel_hi:[1,0,1]
	v_cvt_f32_f16_e32 v0, v140
	v_pk_fma_f32 v[22:23], v[132:133], s[86:87], v[22:23] op_sel_hi:[1,0,1]
	v_cvt_f32_f16_sdwa v1, v140 dst_sel:DWORD dst_unused:UNUSED_PAD src0_sel:WORD_1
	v_cvt_f32_f16_e32 v132, v141
	v_cvt_f32_f16_sdwa v133, v141 dst_sel:DWORD dst_unused:UNUSED_PAD src0_sel:WORD_1
	v_mov_b32_e32 v138, v3
	v_pk_fma_f32 v[12:13], v[0:1], s[86:87], v[12:13] op_sel_hi:[1,0,1]
	v_cvt_f32_f16_e32 v0, v144
	v_pk_fma_f32 v[14:15], v[132:133], s[86:87], v[14:15] op_sel_hi:[1,0,1]
	v_cvt_f32_f16_sdwa v1, v144 dst_sel:DWORD dst_unused:UNUSED_PAD src0_sel:WORD_1
	v_cvt_f32_f16_e32 v132, v145
	v_cvt_f32_f16_sdwa v133, v145 dst_sel:DWORD dst_unused:UNUSED_PAD src0_sel:WORD_1
	v_mov_b32_e32 v139, v3
	v_pk_fma_f32 v[4:5], v[0:1], s[86:87], v[4:5] op_sel_hi:[1,0,1]
	v_cvt_f32_f16_e32 v0, v150
	v_pk_fma_f32 v[6:7], v[132:133], s[86:87], v[6:7] op_sel_hi:[1,0,1]
	v_cvt_f32_f16_sdwa v1, v150 dst_sel:DWORD dst_unused:UNUSED_PAD src0_sel:WORD_1
	v_cvt_f32_f16_e32 v132, v151
	v_cvt_f32_f16_sdwa v133, v151 dst_sel:DWORD dst_unused:UNUSED_PAD src0_sel:WORD_1
	v_pk_fma_f32 v[32:33], v[0:1], s[86:87], v[32:33] op_sel_hi:[1,0,1]
	v_cvt_f32_f16_e32 v0, v178
	v_pk_fma_f32 v[34:35], v[132:133], s[86:87], v[34:35] op_sel_hi:[1,0,1]
	v_cvt_f32_f16_sdwa v1, v178 dst_sel:DWORD dst_unused:UNUSED_PAD src0_sel:WORD_1
	v_cvt_f32_f16_e32 v132, v179
	v_cvt_f32_f16_sdwa v133, v179 dst_sel:DWORD dst_unused:UNUSED_PAD src0_sel:WORD_1
	v_mov_b32_e32 v142, v3
	v_pk_fma_f32 v[24:25], v[0:1], s[86:87], v[24:25] op_sel_hi:[1,0,1]
	v_cvt_f32_f16_e32 v0, v182
	v_pk_fma_f32 v[26:27], v[132:133], s[86:87], v[26:27] op_sel_hi:[1,0,1]
	v_cvt_f32_f16_sdwa v1, v182 dst_sel:DWORD dst_unused:UNUSED_PAD src0_sel:WORD_1
	v_cvt_f32_f16_e32 v132, v183
	v_cvt_f32_f16_sdwa v133, v183 dst_sel:DWORD dst_unused:UNUSED_PAD src0_sel:WORD_1
	v_mov_b32_e32 v143, v3
	v_pk_fma_f32 v[16:17], v[0:1], s[86:87], v[16:17] op_sel_hi:[1,0,1]
	v_cvt_f32_f16_e32 v0, v186
	v_pk_fma_f32 v[18:19], v[132:133], s[86:87], v[18:19] op_sel_hi:[1,0,1]
	v_cvt_f32_f16_sdwa v1, v186 dst_sel:DWORD dst_unused:UNUSED_PAD src0_sel:WORD_1
	v_cvt_f32_f16_e32 v132, v187
	v_cvt_f32_f16_sdwa v133, v187 dst_sel:DWORD dst_unused:UNUSED_PAD src0_sel:WORD_1
	v_mov_b32_e32 v146, v3
	v_pk_fma_f32 v[8:9], v[0:1], s[86:87], v[8:9] op_sel_hi:[1,0,1]
	v_pk_fma_f32 v[10:11], v[132:133], s[86:87], v[10:11] op_sel_hi:[1,0,1]
	v_mov_b32_e32 v147, v3
	v_mov_b32_e32 v152, v3
	v_mov_b32_e32 v153, v3
	v_mov_b32_e32 v180, v3
	v_mov_b32_e32 v181, v3
	v_mov_b32_e32 v184, v3
	v_mov_b32_e32 v185, v3
	v_mov_b32_e32 v188, v3
	v_mov_b32_e32 v189, v3
	s_waitcnt vmcnt(8)
	s_nop 0
	v_cvt_f32_f16_e32 v0, v200
	v_cvt_f32_f16_sdwa v1, v200 dst_sel:DWORD dst_unused:UNUSED_PAD src0_sel:WORD_1
	v_cvt_f32_f16_e32 v200, v201
	v_cvt_f32_f16_sdwa v201, v201 dst_sel:DWORD dst_unused:UNUSED_PAD src0_sel:WORD_1
	v_mov_b32_e32 v146, v3
	v_pk_fma_f32 v[60:61], v[0:1], s[86:87], v[60:61] op_sel_hi:[1,0,1]
	v_cvt_f32_f16_e32 v0, v202
	v_pk_fma_f32 v[62:63], v[200:201], s[86:87], v[62:63] op_sel_hi:[1,0,1]
	v_cvt_f32_f16_sdwa v1, v202 dst_sel:DWORD dst_unused:UNUSED_PAD src0_sel:WORD_1
	v_cvt_f32_f16_e32 v200, v203
	v_cvt_f32_f16_sdwa v201, v203 dst_sel:DWORD dst_unused:UNUSED_PAD src0_sel:WORD_1
	v_mov_b32_e32 v147, v3
	v_pk_fma_f32 v[52:53], v[0:1], s[86:87], v[52:53] op_sel_hi:[1,0,1]
	v_cvt_f32_f16_e32 v0, v204
	v_pk_fma_f32 v[54:55], v[200:201], s[86:87], v[54:55] op_sel_hi:[1,0,1]
	v_cvt_f32_f16_sdwa v1, v204 dst_sel:DWORD dst_unused:UNUSED_PAD src0_sel:WORD_1
	v_cvt_f32_f16_e32 v200, v205
	v_cvt_f32_f16_sdwa v201, v205 dst_sel:DWORD dst_unused:UNUSED_PAD src0_sel:WORD_1
	v_mov_b32_e32 v142, v3
	v_pk_fma_f32 v[44:45], v[0:1], s[86:87], v[44:45] op_sel_hi:[1,0,1]
	v_cvt_f32_f16_e32 v0, v206
	v_pk_fma_f32 v[46:47], v[200:201], s[86:87], v[46:47] op_sel_hi:[1,0,1]
	v_cvt_f32_f16_sdwa v1, v206 dst_sel:DWORD dst_unused:UNUSED_PAD src0_sel:WORD_1
	v_cvt_f32_f16_e32 v200, v207
	v_cvt_f32_f16_sdwa v201, v207 dst_sel:DWORD dst_unused:UNUSED_PAD src0_sel:WORD_1
	v_mov_b32_e32 v143, v3
	v_pk_fma_f32 v[36:37], v[0:1], s[86:87], v[36:37] op_sel_hi:[1,0,1]
	v_cvt_f32_f16_e32 v0, v208
	v_pk_fma_f32 v[38:39], v[200:201], s[86:87], v[38:39] op_sel_hi:[1,0,1]
	v_cvt_f32_f16_sdwa v1, v208 dst_sel:DWORD dst_unused:UNUSED_PAD src0_sel:WORD_1
	v_cvt_f32_f16_e32 v200, v209
	v_cvt_f32_f16_sdwa v201, v209 dst_sel:DWORD dst_unused:UNUSED_PAD src0_sel:WORD_1
	v_pk_fma_f32 v[64:65], v[0:1], s[86:87], v[64:65] op_sel_hi:[1,0,1]
	v_cvt_f32_f16_e32 v0, v210
	v_pk_fma_f32 v[66:67], v[200:201], s[86:87], v[66:67] op_sel_hi:[1,0,1]
	v_cvt_f32_f16_sdwa v1, v210 dst_sel:DWORD dst_unused:UNUSED_PAD src0_sel:WORD_1
	v_cvt_f32_f16_e32 v200, v211
	v_cvt_f32_f16_sdwa v201, v211 dst_sel:DWORD dst_unused:UNUSED_PAD src0_sel:WORD_1
	v_mov_b32_e32 v138, v3
	v_pk_fma_f32 v[56:57], v[0:1], s[86:87], v[56:57] op_sel_hi:[1,0,1]
	v_cvt_f32_f16_e32 v0, v212
	v_pk_fma_f32 v[58:59], v[200:201], s[86:87], v[58:59] op_sel_hi:[1,0,1]
	v_cvt_f32_f16_sdwa v1, v212 dst_sel:DWORD dst_unused:UNUSED_PAD src0_sel:WORD_1
	v_cvt_f32_f16_e32 v200, v213
	v_cvt_f32_f16_sdwa v201, v213 dst_sel:DWORD dst_unused:UNUSED_PAD src0_sel:WORD_1
	v_mov_b32_e32 v139, v3
	v_pk_fma_f32 v[48:49], v[0:1], s[86:87], v[48:49] op_sel_hi:[1,0,1]
	v_cvt_f32_f16_e32 v0, v214
	v_pk_fma_f32 v[50:51], v[200:201], s[86:87], v[50:51] op_sel_hi:[1,0,1]
	v_cvt_f32_f16_sdwa v1, v214 dst_sel:DWORD dst_unused:UNUSED_PAD src0_sel:WORD_1
	v_cvt_f32_f16_e32 v200, v215
	v_cvt_f32_f16_sdwa v201, v215 dst_sel:DWORD dst_unused:UNUSED_PAD src0_sel:WORD_1
	v_mov_b32_e32 v134, v3
	v_pk_fma_f32 v[40:41], v[0:1], s[86:87], v[40:41] op_sel_hi:[1,0,1]
	v_pk_fma_f32 v[42:43], v[200:201], s[86:87], v[42:43] op_sel_hi:[1,0,1]
	v_mov_b32_e32 v135, v3
	v_mov_b32_e32 v152, v3
	v_mov_b32_e32 v153, v3
	v_mov_b32_e32 v180, v3
	v_mov_b32_e32 v181, v3
	v_mov_b32_e32 v184, v3
	v_mov_b32_e32 v185, v3
	v_mov_b32_e32 v188, v3
	v_mov_b32_e32 v189, v3
	s_waitcnt vmcnt(0)
	s_nop 0
	v_cvt_f32_f16_e32 v0, v222
	v_cvt_f32_f16_sdwa v1, v222 dst_sel:DWORD dst_unused:UNUSED_PAD src0_sel:WORD_1
	v_cvt_f32_f16_e32 v134, v223
	v_cvt_f32_f16_sdwa v135, v223 dst_sel:DWORD dst_unused:UNUSED_PAD src0_sel:WORD_1
	v_mov_b32_e32 v142, v3
	v_pk_fma_f32 v[92:93], v[0:1], s[86:87], v[92:93] op_sel_hi:[1,0,1]
	v_cvt_f32_f16_e32 v0, v220
	v_cvt_f32_f16_sdwa v1, v220 dst_sel:DWORD dst_unused:UNUSED_PAD src0_sel:WORD_1
	v_pk_fma_f32 v[94:95], v[134:135], s[86:87], v[94:95] op_sel_hi:[1,0,1]
	v_cvt_f32_f16_e32 v134, v221
	v_cvt_f32_f16_sdwa v135, v221 dst_sel:DWORD dst_unused:UNUSED_PAD src0_sel:WORD_1
	v_pk_fma_f32 v[84:85], v[0:1], s[86:87], v[84:85] op_sel_hi:[1,0,1]
	v_cvt_f32_f16_e32 v0, v218
	v_cvt_f32_f16_sdwa v1, v218 dst_sel:DWORD dst_unused:UNUSED_PAD src0_sel:WORD_1
	v_pk_fma_f32 v[86:87], v[134:135], s[86:87], v[86:87] op_sel_hi:[1,0,1]
	v_cvt_f32_f16_e32 v134, v219
	v_cvt_f32_f16_sdwa v135, v219 dst_sel:DWORD dst_unused:UNUSED_PAD src0_sel:WORD_1
	v_pk_fma_f32 v[76:77], v[0:1], s[86:87], v[76:77] op_sel_hi:[1,0,1]
	v_cvt_f32_f16_e32 v0, v216
	v_cvt_f32_f16_sdwa v1, v216 dst_sel:DWORD dst_unused:UNUSED_PAD src0_sel:WORD_1
	v_cvt_f32_f16_e32 v216, v217
	v_cvt_f32_f16_sdwa v217, v217 dst_sel:DWORD dst_unused:UNUSED_PAD src0_sel:WORD_1
	v_pk_fma_f32 v[78:79], v[134:135], s[86:87], v[78:79] op_sel_hi:[1,0,1]
	v_pk_fma_f32 v[68:69], v[0:1], s[86:87], v[68:69] op_sel_hi:[1,0,1]
	v_cvt_f32_f16_e32 v0, v224
	v_pk_fma_f32 v[70:71], v[216:217], s[86:87], v[70:71] op_sel_hi:[1,0,1]
	v_cvt_f32_f16_sdwa v1, v224 dst_sel:DWORD dst_unused:UNUSED_PAD src0_sel:WORD_1
	v_cvt_f32_f16_e32 v216, v225
	v_cvt_f32_f16_sdwa v217, v225 dst_sel:DWORD dst_unused:UNUSED_PAD src0_sel:WORD_1
	v_pk_fma_f32 v[96:97], v[0:1], s[86:87], v[96:97] op_sel_hi:[1,0,1]
	v_cvt_f32_f16_e32 v0, v226
	v_pk_fma_f32 v[98:99], v[216:217], s[86:87], v[98:99] op_sel_hi:[1,0,1]
	v_cvt_f32_f16_sdwa v1, v226 dst_sel:DWORD dst_unused:UNUSED_PAD src0_sel:WORD_1
	v_cvt_f32_f16_e32 v216, v227
	v_cvt_f32_f16_sdwa v217, v227 dst_sel:DWORD dst_unused:UNUSED_PAD src0_sel:WORD_1
	v_mov_b32_e32 v143, v3
	v_pk_fma_f32 v[88:89], v[0:1], s[86:87], v[88:89] op_sel_hi:[1,0,1]
	v_cvt_f32_f16_e32 v0, v228
	v_pk_fma_f32 v[90:91], v[216:217], s[86:87], v[90:91] op_sel_hi:[1,0,1]
	v_cvt_f32_f16_sdwa v1, v228 dst_sel:DWORD dst_unused:UNUSED_PAD src0_sel:WORD_1
	v_cvt_f32_f16_e32 v216, v229
	v_cvt_f32_f16_sdwa v217, v229 dst_sel:DWORD dst_unused:UNUSED_PAD src0_sel:WORD_1
	v_mov_b32_e32 v138, v3
	v_pk_fma_f32 v[80:81], v[0:1], s[86:87], v[80:81] op_sel_hi:[1,0,1]
	v_cvt_f32_f16_e32 v0, v230
	v_pk_fma_f32 v[82:83], v[216:217], s[86:87], v[82:83] op_sel_hi:[1,0,1]
	v_cvt_f32_f16_sdwa v1, v230 dst_sel:DWORD dst_unused:UNUSED_PAD src0_sel:WORD_1
	v_cvt_f32_f16_e32 v216, v231
	v_cvt_f32_f16_sdwa v217, v231 dst_sel:DWORD dst_unused:UNUSED_PAD src0_sel:WORD_1
	v_mov_b32_e32 v139, v3
	v_pk_fma_f32 v[72:73], v[0:1], s[86:87], v[72:73] op_sel_hi:[1,0,1]
	v_add_u32_e32 v0, 0x28000, v2
	v_pk_fma_f32 v[74:75], v[216:217], s[86:87], v[74:75] op_sel_hi:[1,0,1]
	v_mov_b32_e32 v1, v3
	v_add_u32_e32 v2, 0x2c000, v2
	v_lshl_add_u64 v[132:133], v[0:1], 1, s[2:3]
	v_lshl_add_u64 v[134:135], v[2:3], 1, s[2:3]
	global_load_dwordx2 v[0:1], v[132:133], off
	global_load_dwordx2 v[140:141], v[132:133], off offset:32
	global_load_dwordx2 v[136:137], v[132:133], off offset:256
	s_nop 0
	global_load_dwordx2 v[132:133], v[132:133], off offset:288
	s_nop 0
	global_load_dwordx2 v[144:145], v[134:135], off
	global_load_dwordx2 v[150:151], v[134:135], off offset:32
	global_load_dwordx2 v[178:179], v[134:135], off offset:256
	global_load_dwordx2 v[182:183], v[134:135], off offset:288
	v_mov_b32_e32 v2, v3
	v_mov_b32_e32 v134, v3
	v_mov_b32_e32 v135, v3
	v_mov_b32_e32 v146, v3
	v_mov_b32_e32 v147, v3
	v_mov_b32_e32 v152, v3
	v_mov_b32_e32 v153, v3
	v_mov_b32_e32 v180, v3
	v_mov_b32_e32 v181, v3
	v_mov_b32_e32 v184, v3
	v_mov_b32_e32 v185, v3
	s_lshl_b32 s2, s14, 3
	s_add_i32 s7, s2, 0
	s_waitcnt vmcnt(7)
	v_mov_b64_e32 v[188:189], v[2:3]
	v_mov_b64_e32 v[186:187], v[0:1]
	s_waitcnt vmcnt(0)
	s_nop 0
	v_cvt_f32_f16_e32 v0, v186
	v_cvt_f32_f16_sdwa v1, v186 dst_sel:DWORD dst_unused:UNUSED_PAD src0_sel:WORD_1
	v_cvt_f32_f16_e32 v134, v187
	v_cvt_f32_f16_sdwa v135, v187 dst_sel:DWORD dst_unused:UNUSED_PAD src0_sel:WORD_1
	v_xor_b32_e32 v2, 32, v171
	v_pk_fma_f32 v[124:125], v[0:1], s[86:87], v[124:125] op_sel_hi:[1,0,1]
	v_cvt_f32_f16_e32 v0, v140
	v_cvt_f32_f16_sdwa v1, v140 dst_sel:DWORD dst_unused:UNUSED_PAD src0_sel:WORD_1
	v_pk_fma_f32 v[126:127], v[134:135], s[86:87], v[126:127] op_sel_hi:[1,0,1]
	v_cvt_f32_f16_e32 v134, v141
	v_cvt_f32_f16_sdwa v135, v141 dst_sel:DWORD dst_unused:UNUSED_PAD src0_sel:WORD_1
	v_pk_fma_f32 v[116:117], v[0:1], s[86:87], v[116:117] op_sel_hi:[1,0,1]
	v_cvt_f32_f16_e32 v0, v136
	v_cvt_f32_f16_sdwa v1, v136 dst_sel:DWORD dst_unused:UNUSED_PAD src0_sel:WORD_1
	v_pk_fma_f32 v[118:119], v[134:135], s[86:87], v[118:119] op_sel_hi:[1,0,1]
	v_cvt_f32_f16_e32 v134, v137
	v_cvt_f32_f16_sdwa v135, v137 dst_sel:DWORD dst_unused:UNUSED_PAD src0_sel:WORD_1
	v_pk_fma_f32 v[108:109], v[0:1], s[86:87], v[108:109] op_sel_hi:[1,0,1]
	v_cvt_f32_f16_e32 v0, v132
	v_cvt_f32_f16_sdwa v1, v132 dst_sel:DWORD dst_unused:UNUSED_PAD src0_sel:WORD_1
	v_cvt_f32_f16_e32 v132, v133
	v_cvt_f32_f16_sdwa v133, v133 dst_sel:DWORD dst_unused:UNUSED_PAD src0_sel:WORD_1
	v_pk_fma_f32 v[110:111], v[134:135], s[86:87], v[110:111] op_sel_hi:[1,0,1]
	v_pk_fma_f32 v[100:101], v[0:1], s[86:87], v[100:101] op_sel_hi:[1,0,1]
	v_cvt_f32_f16_e32 v0, v144
	v_cvt_f32_f16_sdwa v1, v144 dst_sel:DWORD dst_unused:UNUSED_PAD src0_sel:WORD_1
	v_pk_fma_f32 v[102:103], v[132:133], s[86:87], v[102:103] op_sel_hi:[1,0,1]
	v_cvt_f32_f16_e32 v132, v145
	v_cvt_f32_f16_sdwa v133, v145 dst_sel:DWORD dst_unused:UNUSED_PAD src0_sel:WORD_1
	v_pk_fma_f32 v[128:129], v[0:1], s[86:87], v[128:129] op_sel_hi:[1,0,1]
	v_cvt_f32_f16_e32 v0, v150
	v_cvt_f32_f16_sdwa v1, v150 dst_sel:DWORD dst_unused:UNUSED_PAD src0_sel:WORD_1
	v_pk_fma_f32 v[130:131], v[132:133], s[86:87], v[130:131] op_sel_hi:[1,0,1]
	v_cvt_f32_f16_e32 v132, v151
	v_cvt_f32_f16_sdwa v133, v151 dst_sel:DWORD dst_unused:UNUSED_PAD src0_sel:WORD_1
	v_pk_fma_f32 v[120:121], v[0:1], s[86:87], v[120:121] op_sel_hi:[1,0,1]
	v_cvt_f32_f16_e32 v0, v178
	v_cvt_f32_f16_sdwa v1, v178 dst_sel:DWORD dst_unused:UNUSED_PAD src0_sel:WORD_1
	v_pk_fma_f32 v[122:123], v[132:133], s[86:87], v[122:123] op_sel_hi:[1,0,1]
	v_cvt_f32_f16_e32 v132, v179
	v_cvt_f32_f16_sdwa v133, v179 dst_sel:DWORD dst_unused:UNUSED_PAD src0_sel:WORD_1
	v_pk_fma_f32 v[112:113], v[0:1], s[86:87], v[112:113] op_sel_hi:[1,0,1]
	v_cvt_f32_f16_e32 v0, v182
	v_cvt_f32_f16_sdwa v1, v182 dst_sel:DWORD dst_unused:UNUSED_PAD src0_sel:WORD_1
	v_pk_fma_f32 v[114:115], v[132:133], s[86:87], v[114:115] op_sel_hi:[1,0,1]
	v_cvt_f32_f16_e32 v132, v183
	v_cvt_f32_f16_sdwa v133, v183 dst_sel:DWORD dst_unused:UNUSED_PAD src0_sel:WORD_1
	v_pk_fma_f32 v[104:105], v[0:1], s[86:87], v[104:105] op_sel_hi:[1,0,1]
	v_and_b32_e32 v1, 64, v171
	v_xor_b32_e32 v0, 16, v171
	v_pk_fma_f32 v[106:107], v[132:133], s[86:87], v[106:107] op_sel_hi:[1,0,1]
	v_add_u32_e32 v1, 64, v1
	v_mov_b32_e32 v132, v29
	v_mov_b32_e32 v133, v30
	v_mov_b32_e32 v134, v28
	v_mov_b32_e32 v135, v31
	v_cmp_lt_i32_e32 vcc, v0, v1
	v_pk_add_f32 v[132:133], v[132:133], v[134:135]
	v_mov_b32_e32 v134, v21
	v_mov_b32_e32 v135, v22
	v_mov_b32_e32 v136, v20
	v_mov_b32_e32 v137, v23
	v_cndmask_b32_e32 v0, v171, v0, vcc
	v_cmp_lt_i32_e32 vcc, v2, v1
	v_pk_add_f32 v[134:135], v[134:135], v[136:137]
	v_add_f32_e32 v137, v12, v13
	v_cndmask_b32_e32 v1, v171, v2, vcc
	v_add_f32_e32 v2, v132, v133
	v_pk_add_f32 v[134:135], v[134:135], v[134:135] op_sel_hi:[0,1]
	v_add_f32_e32 v133, 0, v2
	v_add_f32_e32 v139, v14, v15
	v_mov_b32_e32 v136, v4
	v_mov_b32_e32 v138, v5
	v_mov_b32_e32 v134, v6
	v_mov_b32_e32 v132, v7
	v_pk_add_f32 v[136:137], v[136:137], v[138:139]
	v_pk_add_f32 v[132:133], v[134:135], v[132:133]
	v_lshlrev_b32_e32 v0, 2, v0
	v_pk_add_f32 v[132:133], v[136:137], v[132:133]
	v_lshlrev_b32_e32 v1, 2, v1
	v_add_f32_e32 v2, v132, v133
	v_mov_b32_e32 v132, v2
	s_nop 1
	v_permlane16_swap_b32 v2, v132
	v_cmp_gt_u32_e32 vcc, 16, v149
	s_waitcnt lgkmcnt(0)
	v_add_f32_e32 v2, v2, v132
	v_mov_b32_e32 v132, v2
	s_nop 1
	v_permlane32_swap_b32 v2, v132
	s_waitcnt lgkmcnt(0)
	v_add_f32_e32 v2, v2, v132
	v_fmamk_f32 v133, v2, 0xbc800000, v31
	v_fmamk_f32 v135, v2, 0xbc800000, v29
	v_fmamk_f32 v132, v2, 0xbc800000, v30
	v_fmamk_f32 v134, v2, 0xbc800000, v28
	v_mul_f32_e32 v135, v135, v135
	v_mul_f32_e32 v133, v133, v133
	v_fmac_f32_e32 v135, v134, v134
	v_fmac_f32_e32 v133, v132, v132
	v_fmamk_f32 v134, v2, 0xbc800000, v23
	v_fmamk_f32 v136, v2, 0xbc800000, v21
	v_add_f32_e32 v132, v135, v133
	v_fmamk_f32 v133, v2, 0xbc800000, v22
	v_fmamk_f32 v135, v2, 0xbc800000, v20
	v_mul_f32_e32 v136, v136, v136
	v_mul_f32_e32 v134, v134, v134
	v_fmac_f32_e32 v136, v135, v135
	v_fmac_f32_e32 v134, v133, v133
	v_add_f32_e32 v133, v136, v134
	v_fmamk_f32 v134, v2, 0xbc800000, v15
	v_fmamk_f32 v136, v2, 0xbc800000, v13
	v_add_f32_e32 v132, v132, v133
	v_fmamk_f32 v133, v2, 0xbc800000, v14
	v_fmamk_f32 v135, v2, 0xbc800000, v12
	v_mul_f32_e32 v136, v136, v136
	v_mul_f32_e32 v134, v134, v134
	v_fmac_f32_e32 v136, v135, v135
	v_fmac_f32_e32 v134, v133, v133
	v_add_f32_e32 v133, v136, v134
	v_fmamk_f32 v134, v2, 0xbc800000, v7
	v_fmamk_f32 v136, v2, 0xbc800000, v5
	v_add_f32_e32 v132, v133, v132
	v_fmamk_f32 v133, v2, 0xbc800000, v6
	v_fmamk_f32 v135, v2, 0xbc800000, v4
	v_mul_f32_e32 v136, v136, v136
	v_mul_f32_e32 v134, v134, v134
	v_fmac_f32_e32 v136, v135, v135
	v_fmac_f32_e32 v134, v133, v133
	v_add_f32_e32 v133, v136, v134
	v_add_f32_e32 v132, v133, v132
	v_mov_b32_e32 v133, v132
	s_nop 1
	v_permlane16_swap_b32 v132, v133
	s_waitcnt lgkmcnt(0)
	v_add_f32_e32 v132, v132, v133
	ds_bpermute_b32 v133, v1, v132
	s_and_saveexec_b64 s[4:5], vcc
	s_cbranch_execz .LBB0_508
	s_lshl_b32 s2, s80, 11
	s_add_i32 s2, s7, s2
	v_mul_f32_e32 v134, 0x3c800000, v2
	s_waitcnt lgkmcnt(0)
	v_add_f32_e32 v135, v132, v133
	v_lshl_add_u32 v2, v176, 5, s2
	ds_write_b64 v2, v[134:135]

.LBB0_1154:
	s_lshl_b32 s4, s8, 5
	s_lshl_b32 s5, s44, 8
	s_or_b32 s4, s5, s4
	v_lshrrev_b32_e32 v0, 2, v145
	s_lshl_b32 s6, s1, 8
	v_and_or_b32 v140, v0, 12, s4
	s_add_i32 s4, s6, s14
	v_or_b32_e32 v0, s4, v144
	v_lshl_add_u32 v2, v0, 10, v140
	v_lshl_add_u64 v[0:1], v[2:3], 1, s[64:65]
	global_load_dwordx2 v[132:133], v[0:1], off
	global_load_dwordx2 v[136:137], v[0:1], off offset:32
	global_load_dwordx2 v[146:147], v[0:1], off offset:256
	global_load_dwordx2 v[150:151], v[0:1], off offset:288
	v_add_u32_e32 v0, 0x4000, v2
	v_mov_b32_e32 v1, v3
	v_lshl_add_u64 v[0:1], v[0:1], 1, s[64:65]
	global_load_dwordx2 v[186:187], v[0:1], off
	global_load_dwordx2 v[190:191], v[0:1], off offset:32
	global_load_dwordx2 v[194:195], v[0:1], off offset:256
	global_load_dwordx2 v[198:199], v[0:1], off offset:288
	v_mov_b32_e32 v134, v3
	v_mov_b32_e32 v135, v3
	v_mov_b32_e32 v138, v3
	v_mov_b32_e32 v139, v3
	v_mov_b32_e32 v148, v3
	v_mov_b32_e32 v149, v3
	v_mov_b32_e32 v152, v3
	v_mov_b32_e32 v153, v3
	v_mov_b32_e32 v188, v3
	v_mov_b32_e32 v189, v3
	v_mov_b32_e32 v192, v3
	v_mov_b32_e32 v193, v3
	v_mov_b32_e32 v196, v3
	v_mov_b32_e32 v197, v3
	v_mov_b32_e32 v200, v3
	v_mov_b32_e32 v201, v3
	s_mov_b32 s4, 0x3fd744fd
	v_and_b32_e32 v141, 63, v145
	v_cmp_gt_u32_e32 vcc, 16, v141
	v_add_u32_e32 v0, 0x8000, v2
	v_mov_b32_e32 v1, v3
	v_lshl_add_u64 v[0:1], v[0:1], 1, s[64:65]
	global_load_dwordx2 v[202:203], v[0:1], off
	global_load_dwordx2 v[204:205], v[0:1], off offset:32
	global_load_dwordx2 v[206:207], v[0:1], off offset:256
	global_load_dwordx2 v[208:209], v[0:1], off offset:288
	v_add_u32_e32 v0, 0xc000, v2
	v_mov_b32_e32 v1, v3
	v_lshl_add_u64 v[0:1], v[0:1], 1, s[64:65]
	global_load_dwordx2 v[210:211], v[0:1], off
	global_load_dwordx2 v[212:213], v[0:1], off offset:32
	global_load_dwordx2 v[214:215], v[0:1], off offset:256
	global_load_dwordx2 v[216:217], v[0:1], off offset:288
	v_add_u32_e32 v0, 0x20000, v2
	v_mov_b32_e32 v1, v3
	v_lshl_add_u64 v[0:1], v[0:1], 1, s[64:65]
	global_load_dwordx2 v[220:221], v[0:1], off
	global_load_dwordx2 v[222:223], v[0:1], off offset:32
	global_load_dwordx2 v[224:225], v[0:1], off offset:256
	global_load_dwordx2 v[218:219], v[0:1], off offset:288
	v_add_u32_e32 v0, 0x24000, v2
	v_mov_b32_e32 v1, v3
	v_lshl_add_u64 v[0:1], v[0:1], 1, s[64:65]
	global_load_dwordx2 v[226:227], v[0:1], off
	global_load_dwordx2 v[228:229], v[0:1], off offset:32
	global_load_dwordx2 v[230:231], v[0:1], off offset:256
	global_load_dwordx2 v[232:233], v[0:1], off offset:288
	s_waitcnt vmcnt(24)
	s_barrier
	s_waitcnt vmcnt(16)
	s_nop 0
	v_cvt_f32_f16_e32 v0, v132
	v_cvt_f32_f16_sdwa v1, v132 dst_sel:DWORD dst_unused:UNUSED_PAD src0_sel:WORD_1
	v_cvt_f32_f16_e32 v132, v133
	v_cvt_f32_f16_sdwa v133, v133 dst_sel:DWORD dst_unused:UNUSED_PAD src0_sel:WORD_1
	v_mov_b32_e32 v134, v3
	v_pk_fma_f32 v[36:37], v[0:1], s[4:5], v[36:37] op_sel_hi:[1,0,1]
	v_cvt_f32_f16_e32 v0, v136
	v_pk_fma_f32 v[38:39], v[132:133], s[4:5], v[38:39] op_sel_hi:[1,0,1]
	v_cvt_f32_f16_sdwa v1, v136 dst_sel:DWORD dst_unused:UNUSED_PAD src0_sel:WORD_1
	v_cvt_f32_f16_e32 v132, v137
	v_cvt_f32_f16_sdwa v133, v137 dst_sel:DWORD dst_unused:UNUSED_PAD src0_sel:WORD_1
	v_mov_b32_e32 v135, v3
	v_pk_fma_f32 v[20:21], v[0:1], s[4:5], v[20:21] op_sel_hi:[1,0,1]
	v_cvt_f32_f16_e32 v0, v146
	v_pk_fma_f32 v[22:23], v[132:133], s[4:5], v[22:23] op_sel_hi:[1,0,1]
	v_cvt_f32_f16_sdwa v1, v146 dst_sel:DWORD dst_unused:UNUSED_PAD src0_sel:WORD_1
	v_cvt_f32_f16_e32 v132, v147
	v_cvt_f32_f16_sdwa v133, v147 dst_sel:DWORD dst_unused:UNUSED_PAD src0_sel:WORD_1
	v_mov_b32_e32 v138, v3
	v_pk_fma_f32 v[12:13], v[0:1], s[4:5], v[12:13] op_sel_hi:[1,0,1]
	v_cvt_f32_f16_e32 v0, v150
	v_pk_fma_f32 v[14:15], v[132:133], s[4:5], v[14:15] op_sel_hi:[1,0,1]
	v_cvt_f32_f16_sdwa v1, v150 dst_sel:DWORD dst_unused:UNUSED_PAD src0_sel:WORD_1
	v_cvt_f32_f16_e32 v132, v151
	v_cvt_f32_f16_sdwa v133, v151 dst_sel:DWORD dst_unused:UNUSED_PAD src0_sel:WORD_1
	v_mov_b32_e32 v139, v3
	v_pk_fma_f32 v[4:5], v[0:1], s[4:5], v[4:5] op_sel_hi:[1,0,1]
	v_cvt_f32_f16_e32 v0, v186
	v_pk_fma_f32 v[6:7], v[132:133], s[4:5], v[6:7] op_sel_hi:[1,0,1]
	v_cvt_f32_f16_sdwa v1, v186 dst_sel:DWORD dst_unused:UNUSED_PAD src0_sel:WORD_1
	v_cvt_f32_f16_e32 v132, v187
	v_cvt_f32_f16_sdwa v133, v187 dst_sel:DWORD dst_unused:UNUSED_PAD src0_sel:WORD_1
	v_pk_fma_f32 v[40:41], v[0:1], s[4:5], v[40:41] op_sel_hi:[1,0,1]
	v_cvt_f32_f16_e32 v0, v190
	v_pk_fma_f32 v[42:43], v[132:133], s[4:5], v[42:43] op_sel_hi:[1,0,1]
	v_cvt_f32_f16_sdwa v1, v190 dst_sel:DWORD dst_unused:UNUSED_PAD src0_sel:WORD_1
	v_cvt_f32_f16_e32 v132, v191
	v_cvt_f32_f16_sdwa v133, v191 dst_sel:DWORD dst_unused:UNUSED_PAD src0_sel:WORD_1
	v_mov_b32_e32 v148, v3
	v_pk_fma_f32 v[24:25], v[0:1], s[4:5], v[24:25] op_sel_hi:[1,0,1]
	v_cvt_f32_f16_e32 v0, v194
	v_pk_fma_f32 v[26:27], v[132:133], s[4:5], v[26:27] op_sel_hi:[1,0,1]
	v_cvt_f32_f16_sdwa v1, v194 dst_sel:DWORD dst_unused:UNUSED_PAD src0_sel:WORD_1
	v_cvt_f32_f16_e32 v132, v195
	v_cvt_f32_f16_sdwa v133, v195 dst_sel:DWORD dst_unused:UNUSED_PAD src0_sel:WORD_1
	v_mov_b32_e32 v149, v3
	v_pk_fma_f32 v[16:17], v[0:1], s[4:5], v[16:17] op_sel_hi:[1,0,1]
	v_cvt_f32_f16_e32 v0, v198
	v_pk_fma_f32 v[18:19], v[132:133], s[4:5], v[18:19] op_sel_hi:[1,0,1]
	v_cvt_f32_f16_sdwa v1, v198 dst_sel:DWORD dst_unused:UNUSED_PAD src0_sel:WORD_1
	v_cvt_f32_f16_e32 v132, v199
	v_cvt_f32_f16_sdwa v133, v199 dst_sel:DWORD dst_unused:UNUSED_PAD src0_sel:WORD_1
	v_mov_b32_e32 v152, v3
	v_pk_fma_f32 v[8:9], v[0:1], s[4:5], v[8:9] op_sel_hi:[1,0,1]
	v_pk_fma_f32 v[10:11], v[132:133], s[4:5], v[10:11] op_sel_hi:[1,0,1]
	v_mov_b32_e32 v153, v3
	v_mov_b32_e32 v188, v3
	v_mov_b32_e32 v189, v3
	v_mov_b32_e32 v192, v3
	v_mov_b32_e32 v193, v3
	v_mov_b32_e32 v196, v3
	v_mov_b32_e32 v197, v3
	v_mov_b32_e32 v200, v3
	v_mov_b32_e32 v201, v3
	s_waitcnt vmcnt(8)
	s_nop 0
	v_cvt_f32_f16_e32 v0, v202
	v_cvt_f32_f16_sdwa v1, v202 dst_sel:DWORD dst_unused:UNUSED_PAD src0_sel:WORD_1
	v_cvt_f32_f16_e32 v202, v203
	v_cvt_f32_f16_sdwa v203, v203 dst_sel:DWORD dst_unused:UNUSED_PAD src0_sel:WORD_1
	v_mov_b32_e32 v138, v3
	v_pk_fma_f32 v[100:101], v[0:1], s[4:5], v[100:101] op_sel_hi:[1,0,1]
	v_cvt_f32_f16_e32 v0, v204
	v_pk_fma_f32 v[102:103], v[202:203], s[4:5], v[102:103] op_sel_hi:[1,0,1]
	v_cvt_f32_f16_sdwa v1, v204 dst_sel:DWORD dst_unused:UNUSED_PAD src0_sel:WORD_1
	v_cvt_f32_f16_e32 v202, v205
	v_cvt_f32_f16_sdwa v203, v205 dst_sel:DWORD dst_unused:UNUSED_PAD src0_sel:WORD_1
	v_mov_b32_e32 v139, v3
	v_pk_fma_f32 v[84:85], v[0:1], s[4:5], v[84:85] op_sel_hi:[1,0,1]
	v_cvt_f32_f16_e32 v0, v206
	v_pk_fma_f32 v[86:87], v[202:203], s[4:5], v[86:87] op_sel_hi:[1,0,1]
	v_cvt_f32_f16_sdwa v1, v206 dst_sel:DWORD dst_unused:UNUSED_PAD src0_sel:WORD_1
	v_cvt_f32_f16_e32 v202, v207
	v_cvt_f32_f16_sdwa v203, v207 dst_sel:DWORD dst_unused:UNUSED_PAD src0_sel:WORD_1
	v_mov_b32_e32 v148, v3
	v_pk_fma_f32 v[64:65], v[0:1], s[4:5], v[64:65] op_sel_hi:[1,0,1]
	v_cvt_f32_f16_e32 v0, v208
	v_pk_fma_f32 v[66:67], v[202:203], s[4:5], v[66:67] op_sel_hi:[1,0,1]
	v_cvt_f32_f16_sdwa v1, v208 dst_sel:DWORD dst_unused:UNUSED_PAD src0_sel:WORD_1
	v_cvt_f32_f16_e32 v202, v209
	v_cvt_f32_f16_sdwa v203, v209 dst_sel:DWORD dst_unused:UNUSED_PAD src0_sel:WORD_1
	v_mov_b32_e32 v149, v3
	v_pk_fma_f32 v[32:33], v[0:1], s[4:5], v[32:33] op_sel_hi:[1,0,1]
	v_cvt_f32_f16_e32 v0, v210
	v_pk_fma_f32 v[34:35], v[202:203], s[4:5], v[34:35] op_sel_hi:[1,0,1]
	v_cvt_f32_f16_sdwa v1, v210 dst_sel:DWORD dst_unused:UNUSED_PAD src0_sel:WORD_1
	v_cvt_f32_f16_e32 v202, v211
	v_cvt_f32_f16_sdwa v203, v211 dst_sel:DWORD dst_unused:UNUSED_PAD src0_sel:WORD_1
	v_pk_fma_f32 v[104:105], v[0:1], s[4:5], v[104:105] op_sel_hi:[1,0,1]
	v_cvt_f32_f16_e32 v0, v212
	v_pk_fma_f32 v[106:107], v[202:203], s[4:5], v[106:107] op_sel_hi:[1,0,1]
	v_cvt_f32_f16_sdwa v1, v212 dst_sel:DWORD dst_unused:UNUSED_PAD src0_sel:WORD_1
	v_cvt_f32_f16_e32 v202, v213
	v_cvt_f32_f16_sdwa v203, v213 dst_sel:DWORD dst_unused:UNUSED_PAD src0_sel:WORD_1
	v_mov_b32_e32 v152, v3
	v_pk_fma_f32 v[88:89], v[0:1], s[4:5], v[88:89] op_sel_hi:[1,0,1]
	v_cvt_f32_f16_e32 v0, v214
	v_pk_fma_f32 v[90:91], v[202:203], s[4:5], v[90:91] op_sel_hi:[1,0,1]
	v_cvt_f32_f16_sdwa v1, v214 dst_sel:DWORD dst_unused:UNUSED_PAD src0_sel:WORD_1
	v_cvt_f32_f16_e32 v202, v215
	v_cvt_f32_f16_sdwa v203, v215 dst_sel:DWORD dst_unused:UNUSED_PAD src0_sel:WORD_1
	v_mov_b32_e32 v153, v3
	v_pk_fma_f32 v[68:69], v[0:1], s[4:5], v[68:69] op_sel_hi:[1,0,1]
	v_cvt_f32_f16_e32 v0, v216
	v_pk_fma_f32 v[70:71], v[202:203], s[4:5], v[70:71] op_sel_hi:[1,0,1]
	v_cvt_f32_f16_sdwa v1, v216 dst_sel:DWORD dst_unused:UNUSED_PAD src0_sel:WORD_1
	v_cvt_f32_f16_e32 v202, v217
	v_cvt_f32_f16_sdwa v203, v217 dst_sel:DWORD dst_unused:UNUSED_PAD src0_sel:WORD_1
	v_mov_b32_e32 v134, v3
	v_pk_fma_f32 v[28:29], v[0:1], s[4:5], v[28:29] op_sel_hi:[1,0,1]
	v_pk_fma_f32 v[30:31], v[202:203], s[4:5], v[30:31] op_sel_hi:[1,0,1]
	v_mov_b32_e32 v135, v3
	v_mov_b32_e32 v188, v3
	v_mov_b32_e32 v189, v3
	v_mov_b32_e32 v192, v3
	v_mov_b32_e32 v193, v3
	v_mov_b32_e32 v196, v3
	v_mov_b32_e32 v197, v3
	v_mov_b32_e32 v200, v3
	v_mov_b32_e32 v201, v3
	s_waitcnt vmcnt(0)
	s_nop 0
	v_cvt_f32_f16_e32 v0, v220
	v_cvt_f32_f16_sdwa v1, v220 dst_sel:DWORD dst_unused:UNUSED_PAD src0_sel:WORD_1
	v_cvt_f32_f16_e32 v134, v221
	v_cvt_f32_f16_sdwa v135, v221 dst_sel:DWORD dst_unused:UNUSED_PAD src0_sel:WORD_1
	v_mov_b32_e32 v148, v3
	v_pk_fma_f32 v[128:129], v[0:1], s[4:5], v[128:129] op_sel_hi:[1,0,1]
	v_cvt_f32_f16_e32 v0, v222
	v_cvt_f32_f16_sdwa v1, v222 dst_sel:DWORD dst_unused:UNUSED_PAD src0_sel:WORD_1
	v_pk_fma_f32 v[130:131], v[134:135], s[4:5], v[130:131] op_sel_hi:[1,0,1]
	v_cvt_f32_f16_e32 v134, v223
	v_cvt_f32_f16_sdwa v135, v223 dst_sel:DWORD dst_unused:UNUSED_PAD src0_sel:WORD_1
	v_pk_fma_f32 v[124:125], v[0:1], s[4:5], v[124:125] op_sel_hi:[1,0,1]
	v_cvt_f32_f16_e32 v0, v224
	v_cvt_f32_f16_sdwa v1, v224 dst_sel:DWORD dst_unused:UNUSED_PAD src0_sel:WORD_1
	v_pk_fma_f32 v[126:127], v[134:135], s[4:5], v[126:127] op_sel_hi:[1,0,1]
	v_cvt_f32_f16_e32 v134, v225
	v_cvt_f32_f16_sdwa v135, v225 dst_sel:DWORD dst_unused:UNUSED_PAD src0_sel:WORD_1
	v_pk_fma_f32 v[108:109], v[0:1], s[4:5], v[108:109] op_sel_hi:[1,0,1]
	v_cvt_f32_f16_e32 v0, v218
	v_cvt_f32_f16_sdwa v1, v218 dst_sel:DWORD dst_unused:UNUSED_PAD src0_sel:WORD_1
	v_cvt_f32_f16_e32 v218, v219
	v_cvt_f32_f16_sdwa v219, v219 dst_sel:DWORD dst_unused:UNUSED_PAD src0_sel:WORD_1
	v_pk_fma_f32 v[110:111], v[134:135], s[4:5], v[110:111] op_sel_hi:[1,0,1]
	v_pk_fma_f32 v[92:93], v[0:1], s[4:5], v[92:93] op_sel_hi:[1,0,1]
	v_cvt_f32_f16_e32 v0, v226
	v_pk_fma_f32 v[94:95], v[218:219], s[4:5], v[94:95] op_sel_hi:[1,0,1]
	v_cvt_f32_f16_sdwa v1, v226 dst_sel:DWORD dst_unused:UNUSED_PAD src0_sel:WORD_1
	v_cvt_f32_f16_e32 v218, v227
	v_cvt_f32_f16_sdwa v219, v227 dst_sel:DWORD dst_unused:UNUSED_PAD src0_sel:WORD_1
	v_pk_fma_f32 v[120:121], v[0:1], s[4:5], v[120:121] op_sel_hi:[1,0,1]
	v_cvt_f32_f16_e32 v0, v228
	v_pk_fma_f32 v[122:123], v[218:219], s[4:5], v[122:123] op_sel_hi:[1,0,1]
	v_cvt_f32_f16_sdwa v1, v228 dst_sel:DWORD dst_unused:UNUSED_PAD src0_sel:WORD_1
	v_cvt_f32_f16_e32 v218, v229
	v_cvt_f32_f16_sdwa v219, v229 dst_sel:DWORD dst_unused:UNUSED_PAD src0_sel:WORD_1
	v_mov_b32_e32 v149, v3
	v_pk_fma_f32 v[116:117], v[0:1], s[4:5], v[116:117] op_sel_hi:[1,0,1]
	v_cvt_f32_f16_e32 v0, v230
	v_pk_fma_f32 v[118:119], v[218:219], s[4:5], v[118:119] op_sel_hi:[1,0,1]
	v_cvt_f32_f16_sdwa v1, v230 dst_sel:DWORD dst_unused:UNUSED_PAD src0_sel:WORD_1
	v_cvt_f32_f16_e32 v218, v231
	v_cvt_f32_f16_sdwa v219, v231 dst_sel:DWORD dst_unused:UNUSED_PAD src0_sel:WORD_1
	v_mov_b32_e32 v138, v3
	v_pk_fma_f32 v[112:113], v[0:1], s[4:5], v[112:113] op_sel_hi:[1,0,1]
	v_cvt_f32_f16_e32 v0, v232
	v_pk_fma_f32 v[114:115], v[218:219], s[4:5], v[114:115] op_sel_hi:[1,0,1]
	v_cvt_f32_f16_sdwa v1, v232 dst_sel:DWORD dst_unused:UNUSED_PAD src0_sel:WORD_1
	v_cvt_f32_f16_e32 v218, v233
	v_cvt_f32_f16_sdwa v219, v233 dst_sel:DWORD dst_unused:UNUSED_PAD src0_sel:WORD_1
	v_mov_b32_e32 v139, v3
	v_pk_fma_f32 v[96:97], v[0:1], s[4:5], v[96:97] op_sel_hi:[1,0,1]
	v_add_u32_e32 v0, 0x28000, v2
	v_pk_fma_f32 v[98:99], v[218:219], s[4:5], v[98:99] op_sel_hi:[1,0,1]
	v_mov_b32_e32 v1, v3
	v_add_u32_e32 v2, 0x2c000, v2
	v_lshl_add_u64 v[132:133], v[0:1], 1, s[64:65]
	v_lshl_add_u64 v[134:135], v[2:3], 1, s[64:65]
	global_load_dwordx2 v[0:1], v[132:133], off
	global_load_dwordx2 v[146:147], v[132:133], off offset:32
	global_load_dwordx2 v[136:137], v[132:133], off offset:256
	s_nop 0
	global_load_dwordx2 v[132:133], v[132:133], off offset:288
	s_nop 0
	global_load_dwordx2 v[150:151], v[134:135], off
	global_load_dwordx2 v[186:187], v[134:135], off offset:32
	global_load_dwordx2 v[190:191], v[134:135], off offset:256
	global_load_dwordx2 v[194:195], v[134:135], off offset:288
	v_mov_b32_e32 v2, v3
	v_mov_b32_e32 v134, v3
	v_mov_b32_e32 v135, v3
	v_mov_b32_e32 v152, v3
	v_mov_b32_e32 v153, v3
	v_mov_b32_e32 v188, v3
	v_mov_b32_e32 v189, v3
	v_mov_b32_e32 v192, v3
	v_mov_b32_e32 v193, v3
	v_mov_b32_e32 v196, v3
	v_mov_b32_e32 v197, v3
	s_waitcnt vmcnt(7)
	v_mov_b64_e32 v[200:201], v[2:3]
	v_mov_b64_e32 v[198:199], v[0:1]
	s_waitcnt vmcnt(0)
	s_nop 0
	v_cvt_f32_f16_e32 v0, v198
	v_cvt_f32_f16_sdwa v1, v198 dst_sel:DWORD dst_unused:UNUSED_PAD src0_sel:WORD_1
	v_cvt_f32_f16_e32 v134, v199
	v_cvt_f32_f16_sdwa v135, v199 dst_sel:DWORD dst_unused:UNUSED_PAD src0_sel:WORD_1
	v_pk_fma_f32 v[80:81], v[0:1], s[4:5], v[80:81] op_sel_hi:[1,0,1]
	v_cvt_f32_f16_e32 v0, v146
	v_cvt_f32_f16_sdwa v1, v146 dst_sel:DWORD dst_unused:UNUSED_PAD src0_sel:WORD_1
	v_pk_fma_f32 v[82:83], v[134:135], s[4:5], v[82:83] op_sel_hi:[1,0,1]
	v_cvt_f32_f16_e32 v134, v147
	v_cvt_f32_f16_sdwa v135, v147 dst_sel:DWORD dst_unused:UNUSED_PAD src0_sel:WORD_1
	v_pk_fma_f32 v[76:77], v[0:1], s[4:5], v[76:77] op_sel_hi:[1,0,1]
	v_cvt_f32_f16_e32 v0, v136
	v_cvt_f32_f16_sdwa v1, v136 dst_sel:DWORD dst_unused:UNUSED_PAD src0_sel:WORD_1
	v_pk_fma_f32 v[78:79], v[134:135], s[4:5], v[78:79] op_sel_hi:[1,0,1]
	v_cvt_f32_f16_e32 v134, v137
	v_cvt_f32_f16_sdwa v135, v137 dst_sel:DWORD dst_unused:UNUSED_PAD src0_sel:WORD_1
	v_pk_fma_f32 v[56:57], v[0:1], s[4:5], v[56:57] op_sel_hi:[1,0,1]
	v_cvt_f32_f16_e32 v0, v132
	v_cvt_f32_f16_sdwa v1, v132 dst_sel:DWORD dst_unused:UNUSED_PAD src0_sel:WORD_1
	v_cvt_f32_f16_e32 v132, v133
	v_cvt_f32_f16_sdwa v133, v133 dst_sel:DWORD dst_unused:UNUSED_PAD src0_sel:WORD_1
	v_pk_fma_f32 v[58:59], v[134:135], s[4:5], v[58:59] op_sel_hi:[1,0,1]
	v_pk_fma_f32 v[52:53], v[0:1], s[4:5], v[52:53] op_sel_hi:[1,0,1]
	v_cvt_f32_f16_e32 v0, v150
	v_pk_fma_f32 v[54:55], v[132:133], s[4:5], v[54:55] op_sel_hi:[1,0,1]
	v_cvt_f32_f16_sdwa v1, v150 dst_sel:DWORD dst_unused:UNUSED_PAD src0_sel:WORD_1
	v_cvt_f32_f16_e32 v132, v151
	v_cvt_f32_f16_sdwa v133, v151 dst_sel:DWORD dst_unused:UNUSED_PAD src0_sel:WORD_1
	v_mov_b32_e32 v134, v20
	v_pk_fma_f32 v[72:73], v[0:1], s[4:5], v[72:73] op_sel_hi:[1,0,1]
	v_cvt_f32_f16_e32 v0, v186
	v_pk_fma_f32 v[74:75], v[132:133], s[4:5], v[74:75] op_sel_hi:[1,0,1]
	v_cvt_f32_f16_sdwa v1, v186 dst_sel:DWORD dst_unused:UNUSED_PAD src0_sel:WORD_1
	v_cvt_f32_f16_e32 v132, v187
	v_cvt_f32_f16_sdwa v133, v187 dst_sel:DWORD dst_unused:UNUSED_PAD src0_sel:WORD_1
	v_mov_b32_e32 v135, v23
	v_pk_fma_f32 v[60:61], v[0:1], s[4:5], v[60:61] op_sel_hi:[1,0,1]
	v_cvt_f32_f16_e32 v0, v190
	v_pk_fma_f32 v[62:63], v[132:133], s[4:5], v[62:63] op_sel_hi:[1,0,1]
	v_cvt_f32_f16_sdwa v1, v190 dst_sel:DWORD dst_unused:UNUSED_PAD src0_sel:WORD_1
	v_cvt_f32_f16_e32 v132, v191
	v_cvt_f32_f16_sdwa v133, v191 dst_sel:DWORD dst_unused:UNUSED_PAD src0_sel:WORD_1
	v_add_f32_e32 v137, v14, v15
	v_pk_fma_f32 v[48:49], v[0:1], s[4:5], v[48:49] op_sel_hi:[1,0,1]
	v_cvt_f32_f16_e32 v0, v194
	v_pk_fma_f32 v[50:51], v[132:133], s[4:5], v[50:51] op_sel_hi:[1,0,1]
	v_cvt_f32_f16_sdwa v1, v194 dst_sel:DWORD dst_unused:UNUSED_PAD src0_sel:WORD_1
	v_cvt_f32_f16_e32 v132, v195
	v_cvt_f32_f16_sdwa v133, v195 dst_sel:DWORD dst_unused:UNUSED_PAD src0_sel:WORD_1
	v_mov_b32_e32 v136, v5
	v_pk_fma_f32 v[44:45], v[0:1], s[4:5], v[44:45] op_sel_hi:[1,0,1]
	v_mov_b32_e32 v0, v37
	v_pk_fma_f32 v[46:47], v[132:133], s[4:5], v[46:47] op_sel_hi:[1,0,1]
	v_mov_b32_e32 v1, v38
	v_mov_b32_e32 v132, v36
	v_mov_b32_e32 v133, v39
	v_pk_add_f32 v[0:1], v[0:1], v[132:133]
	v_mov_b32_e32 v132, v21
	v_mov_b32_e32 v133, v22
	v_pk_add_f32 v[132:133], v[132:133], v[134:135]
	v_add_f32_e32 v0, v0, v1
	v_pk_add_f32 v[132:133], v[132:133], v[132:133] op_sel_hi:[0,1]
	v_add_f32_e32 v1, 0, v0
	v_add_f32_e32 v135, v12, v13
	v_mov_b32_e32 v134, v4
	v_mov_b32_e32 v132, v6
	v_mov_b32_e32 v0, v7
	v_pk_add_f32 v[134:135], v[134:135], v[136:137]
	v_pk_add_f32 v[0:1], v[132:133], v[0:1]
	s_lshl_b32 s4, s8, 3
	v_pk_add_f32 v[0:1], v[134:135], v[0:1]
	s_add_i32 s7, s4, 0
	v_add_f32_e32 v0, v0, v1
	v_mov_b32_e32 v1, v0
	s_nop 1
	v_permlane16_swap_b32 v0, v1
	s_waitcnt lgkmcnt(0)
	v_add_f32_e32 v0, v0, v1
	v_mov_b32_e32 v1, v0
	s_nop 1
	v_permlane32_swap_b32 v0, v1
	s_waitcnt lgkmcnt(0)
	v_add_f32_e32 v0, v0, v1
	v_fmamk_f32 v2, v0, 0xbc800000, v39
	v_fmamk_f32 v133, v0, 0xbc800000, v37
	v_fmamk_f32 v1, v0, 0xbc800000, v38
	v_fmamk_f32 v132, v0, 0xbc800000, v36
	v_mul_f32_e32 v133, v133, v133
	v_mul_f32_e32 v2, v2, v2
	v_fmac_f32_e32 v133, v132, v132
	v_fmac_f32_e32 v2, v1, v1
	v_fmamk_f32 v132, v0, 0xbc800000, v23
	v_fmamk_f32 v134, v0, 0xbc800000, v21
	v_add_f32_e32 v1, v133, v2
	v_fmamk_f32 v2, v0, 0xbc800000, v22
	v_fmamk_f32 v133, v0, 0xbc800000, v20
	v_mul_f32_e32 v134, v134, v134
	v_mul_f32_e32 v132, v132, v132
	v_fmac_f32_e32 v134, v133, v133
	v_fmac_f32_e32 v132, v2, v2
	v_add_f32_e32 v2, v134, v132
	v_fmamk_f32 v132, v0, 0xbc800000, v15
	v_fmamk_f32 v134, v0, 0xbc800000, v13
	v_add_f32_e32 v1, v1, v2
	v_fmamk_f32 v2, v0, 0xbc800000, v14
	v_fmamk_f32 v133, v0, 0xbc800000, v12
	v_mul_f32_e32 v134, v134, v134
	v_mul_f32_e32 v132, v132, v132
	v_fmac_f32_e32 v134, v133, v133
	v_fmac_f32_e32 v132, v2, v2
	v_add_f32_e32 v2, v134, v132
	v_fmamk_f32 v132, v0, 0xbc800000, v7
	v_fmamk_f32 v134, v0, 0xbc800000, v5
	v_add_f32_e32 v1, v2, v1
	v_fmamk_f32 v2, v0, 0xbc800000, v6
	v_fmamk_f32 v133, v0, 0xbc800000, v4
	v_mul_f32_e32 v134, v134, v134
	v_mul_f32_e32 v132, v132, v132
	v_fmac_f32_e32 v134, v133, v133
	v_fmac_f32_e32 v132, v2, v2
	v_add_f32_e32 v2, v134, v132
	v_add_f32_e32 v1, v2, v1
	v_mov_b32_e32 v2, v1
	s_nop 1
	v_permlane16_swap_b32 v1, v2
	s_waitcnt lgkmcnt(0)
	v_add_f32_e32 v1, v1, v2
	v_mov_b32_e32 v2, v1
	s_nop 1
	v_permlane32_swap_b32 v1, v2
	s_and_saveexec_b64 s[4:5], vcc
	s_cbranch_execz .LBB0_1156
	s_lshl_b32 s8, s0, 11
	s_add_i32 s8, s7, s8
	v_mul_f32_e32 v0, 0x3c800000, v0
	s_waitcnt lgkmcnt(0)
	v_add_f32_e32 v1, v1, v2
	v_lshl_add_u32 v2, v144, 5, s8
	ds_write_b64 v2, v[0:1]

.LBB0_1210:
	s_lshl_b32 s4, s8, 5
	s_lshl_b32 s5, s44, 8
	s_or_b32 s4, s5, s4
	v_lshrrev_b32_e32 v0, 2, v145
	s_lshl_b32 s6, s1, 8
	v_and_or_b32 v140, v0, 12, s4
	s_add_i32 s4, s6, s14
	v_or_b32_e32 v0, s4, v144
	v_lshl_add_u32 v2, v0, 10, v140
	v_lshl_add_u64 v[0:1], v[2:3], 1, s[64:65]
	global_load_dwordx2 v[132:133], v[0:1], off
	global_load_dwordx2 v[136:137], v[0:1], off offset:32
	global_load_dwordx2 v[146:147], v[0:1], off offset:256
	global_load_dwordx2 v[150:151], v[0:1], off offset:288
	v_add_u32_e32 v0, 0x4000, v2
	v_mov_b32_e32 v1, v3
	v_lshl_add_u64 v[0:1], v[0:1], 1, s[64:65]
	global_load_dwordx2 v[186:187], v[0:1], off
	global_load_dwordx2 v[190:191], v[0:1], off offset:32
	global_load_dwordx2 v[194:195], v[0:1], off offset:256
	global_load_dwordx2 v[198:199], v[0:1], off offset:288
	v_mov_b32_e32 v134, v3
	v_mov_b32_e32 v135, v3
	v_mov_b32_e32 v138, v3
	v_mov_b32_e32 v139, v3
	v_mov_b32_e32 v148, v3
	v_mov_b32_e32 v149, v3
	v_mov_b32_e32 v152, v3
	v_mov_b32_e32 v153, v3
	v_mov_b32_e32 v188, v3
	v_mov_b32_e32 v189, v3
	v_mov_b32_e32 v192, v3
	v_mov_b32_e32 v193, v3
	v_mov_b32_e32 v196, v3
	v_mov_b32_e32 v197, v3
	v_mov_b32_e32 v200, v3
	v_mov_b32_e32 v201, v3
	s_mov_b32 s4, 0x3fd744fd
	v_and_b32_e32 v141, 63, v145
	v_cmp_gt_u32_e32 vcc, 16, v141
	v_add_u32_e32 v0, 0x8000, v2
	v_mov_b32_e32 v1, v3
	v_lshl_add_u64 v[0:1], v[0:1], 1, s[64:65]
	global_load_dwordx2 v[202:203], v[0:1], off
	global_load_dwordx2 v[204:205], v[0:1], off offset:32
	global_load_dwordx2 v[206:207], v[0:1], off offset:256
	global_load_dwordx2 v[208:209], v[0:1], off offset:288
	v_add_u32_e32 v0, 0xc000, v2
	v_mov_b32_e32 v1, v3
	v_lshl_add_u64 v[0:1], v[0:1], 1, s[64:65]
	global_load_dwordx2 v[210:211], v[0:1], off
	global_load_dwordx2 v[212:213], v[0:1], off offset:32
	global_load_dwordx2 v[214:215], v[0:1], off offset:256
	global_load_dwordx2 v[216:217], v[0:1], off offset:288
	v_add_u32_e32 v0, 0x20000, v2
	v_mov_b32_e32 v1, v3
	v_lshl_add_u64 v[0:1], v[0:1], 1, s[64:65]
	global_load_dwordx2 v[220:221], v[0:1], off
	global_load_dwordx2 v[222:223], v[0:1], off offset:32
	global_load_dwordx2 v[224:225], v[0:1], off offset:256
	global_load_dwordx2 v[218:219], v[0:1], off offset:288
	v_add_u32_e32 v0, 0x24000, v2
	v_mov_b32_e32 v1, v3
	v_lshl_add_u64 v[0:1], v[0:1], 1, s[64:65]
	global_load_dwordx2 v[226:227], v[0:1], off
	global_load_dwordx2 v[228:229], v[0:1], off offset:32
	global_load_dwordx2 v[230:231], v[0:1], off offset:256
	global_load_dwordx2 v[232:233], v[0:1], off offset:288
	s_waitcnt vmcnt(24)
	s_barrier
	s_waitcnt vmcnt(16)
	s_nop 0
	v_cvt_f32_f16_e32 v0, v132
	v_cvt_f32_f16_sdwa v1, v132 dst_sel:DWORD dst_unused:UNUSED_PAD src0_sel:WORD_1
	v_cvt_f32_f16_e32 v132, v133
	v_cvt_f32_f16_sdwa v133, v133 dst_sel:DWORD dst_unused:UNUSED_PAD src0_sel:WORD_1
	v_mov_b32_e32 v134, v3
	v_pk_fma_f32 v[36:37], v[0:1], s[4:5], v[36:37] op_sel_hi:[1,0,1]
	v_cvt_f32_f16_e32 v0, v136
	v_pk_fma_f32 v[38:39], v[132:133], s[4:5], v[38:39] op_sel_hi:[1,0,1]
	v_cvt_f32_f16_sdwa v1, v136 dst_sel:DWORD dst_unused:UNUSED_PAD src0_sel:WORD_1
	v_cvt_f32_f16_e32 v132, v137
	v_cvt_f32_f16_sdwa v133, v137 dst_sel:DWORD dst_unused:UNUSED_PAD src0_sel:WORD_1
	v_mov_b32_e32 v135, v3
	v_pk_fma_f32 v[24:25], v[0:1], s[4:5], v[24:25] op_sel_hi:[1,0,1]
	v_cvt_f32_f16_e32 v0, v146
	v_pk_fma_f32 v[26:27], v[132:133], s[4:5], v[26:27] op_sel_hi:[1,0,1]
	v_cvt_f32_f16_sdwa v1, v146 dst_sel:DWORD dst_unused:UNUSED_PAD src0_sel:WORD_1
	v_cvt_f32_f16_e32 v132, v147
	v_cvt_f32_f16_sdwa v133, v147 dst_sel:DWORD dst_unused:UNUSED_PAD src0_sel:WORD_1
	v_mov_b32_e32 v138, v3
	v_pk_fma_f32 v[16:17], v[0:1], s[4:5], v[16:17] op_sel_hi:[1,0,1]
	v_cvt_f32_f16_e32 v0, v150
	v_pk_fma_f32 v[18:19], v[132:133], s[4:5], v[18:19] op_sel_hi:[1,0,1]
	v_cvt_f32_f16_sdwa v1, v150 dst_sel:DWORD dst_unused:UNUSED_PAD src0_sel:WORD_1
	v_cvt_f32_f16_e32 v132, v151
	v_cvt_f32_f16_sdwa v133, v151 dst_sel:DWORD dst_unused:UNUSED_PAD src0_sel:WORD_1
	v_mov_b32_e32 v139, v3
	v_pk_fma_f32 v[8:9], v[0:1], s[4:5], v[8:9] op_sel_hi:[1,0,1]
	v_cvt_f32_f16_e32 v0, v186
	v_pk_fma_f32 v[10:11], v[132:133], s[4:5], v[10:11] op_sel_hi:[1,0,1]
	v_cvt_f32_f16_sdwa v1, v186 dst_sel:DWORD dst_unused:UNUSED_PAD src0_sel:WORD_1
	v_cvt_f32_f16_e32 v132, v187
	v_cvt_f32_f16_sdwa v133, v187 dst_sel:DWORD dst_unused:UNUSED_PAD src0_sel:WORD_1
	v_pk_fma_f32 v[40:41], v[0:1], s[4:5], v[40:41] op_sel_hi:[1,0,1]
	v_cvt_f32_f16_e32 v0, v190
	v_pk_fma_f32 v[42:43], v[132:133], s[4:5], v[42:43] op_sel_hi:[1,0,1]
	v_cvt_f32_f16_sdwa v1, v190 dst_sel:DWORD dst_unused:UNUSED_PAD src0_sel:WORD_1
	v_cvt_f32_f16_e32 v132, v191
	v_cvt_f32_f16_sdwa v133, v191 dst_sel:DWORD dst_unused:UNUSED_PAD src0_sel:WORD_1
	v_mov_b32_e32 v148, v3
	v_pk_fma_f32 v[20:21], v[0:1], s[4:5], v[20:21] op_sel_hi:[1,0,1]
	v_cvt_f32_f16_e32 v0, v194
	v_pk_fma_f32 v[22:23], v[132:133], s[4:5], v[22:23] op_sel_hi:[1,0,1]
	v_cvt_f32_f16_sdwa v1, v194 dst_sel:DWORD dst_unused:UNUSED_PAD src0_sel:WORD_1
	v_cvt_f32_f16_e32 v132, v195
	v_cvt_f32_f16_sdwa v133, v195 dst_sel:DWORD dst_unused:UNUSED_PAD src0_sel:WORD_1
	v_mov_b32_e32 v149, v3
	v_pk_fma_f32 v[12:13], v[0:1], s[4:5], v[12:13] op_sel_hi:[1,0,1]
	v_cvt_f32_f16_e32 v0, v198
	v_pk_fma_f32 v[14:15], v[132:133], s[4:5], v[14:15] op_sel_hi:[1,0,1]
	v_cvt_f32_f16_sdwa v1, v198 dst_sel:DWORD dst_unused:UNUSED_PAD src0_sel:WORD_1
	v_cvt_f32_f16_e32 v132, v199
	v_cvt_f32_f16_sdwa v133, v199 dst_sel:DWORD dst_unused:UNUSED_PAD src0_sel:WORD_1
	v_mov_b32_e32 v152, v3
	v_pk_fma_f32 v[4:5], v[0:1], s[4:5], v[4:5] op_sel_hi:[1,0,1]
	v_pk_fma_f32 v[6:7], v[132:133], s[4:5], v[6:7] op_sel_hi:[1,0,1]
	v_mov_b32_e32 v153, v3
	v_mov_b32_e32 v188, v3
	v_mov_b32_e32 v189, v3
	v_mov_b32_e32 v192, v3
	v_mov_b32_e32 v193, v3
	v_mov_b32_e32 v196, v3
	v_mov_b32_e32 v197, v3
	v_mov_b32_e32 v200, v3
	v_mov_b32_e32 v201, v3
	s_waitcnt vmcnt(8)
	s_nop 0
	v_cvt_f32_f16_e32 v0, v202
	v_cvt_f32_f16_sdwa v1, v202 dst_sel:DWORD dst_unused:UNUSED_PAD src0_sel:WORD_1
	v_cvt_f32_f16_e32 v202, v203
	v_cvt_f32_f16_sdwa v203, v203 dst_sel:DWORD dst_unused:UNUSED_PAD src0_sel:WORD_1
	v_mov_b32_e32 v138, v3
	v_pk_fma_f32 v[100:101], v[0:1], s[4:5], v[100:101] op_sel_hi:[1,0,1]
	v_cvt_f32_f16_e32 v0, v204
	v_pk_fma_f32 v[102:103], v[202:203], s[4:5], v[102:103] op_sel_hi:[1,0,1]
	v_cvt_f32_f16_sdwa v1, v204 dst_sel:DWORD dst_unused:UNUSED_PAD src0_sel:WORD_1
	v_cvt_f32_f16_e32 v202, v205
	v_cvt_f32_f16_sdwa v203, v205 dst_sel:DWORD dst_unused:UNUSED_PAD src0_sel:WORD_1
	v_mov_b32_e32 v139, v3
	v_pk_fma_f32 v[88:89], v[0:1], s[4:5], v[88:89] op_sel_hi:[1,0,1]
	v_cvt_f32_f16_e32 v0, v206
	v_pk_fma_f32 v[90:91], v[202:203], s[4:5], v[90:91] op_sel_hi:[1,0,1]
	v_cvt_f32_f16_sdwa v1, v206 dst_sel:DWORD dst_unused:UNUSED_PAD src0_sel:WORD_1
	v_cvt_f32_f16_e32 v202, v207
	v_cvt_f32_f16_sdwa v203, v207 dst_sel:DWORD dst_unused:UNUSED_PAD src0_sel:WORD_1
	v_mov_b32_e32 v148, v3
	v_pk_fma_f32 v[52:53], v[0:1], s[4:5], v[52:53] op_sel_hi:[1,0,1]
	v_cvt_f32_f16_e32 v0, v208
	v_pk_fma_f32 v[54:55], v[202:203], s[4:5], v[54:55] op_sel_hi:[1,0,1]
	v_cvt_f32_f16_sdwa v1, v208 dst_sel:DWORD dst_unused:UNUSED_PAD src0_sel:WORD_1
	v_cvt_f32_f16_e32 v202, v209
	v_cvt_f32_f16_sdwa v203, v209 dst_sel:DWORD dst_unused:UNUSED_PAD src0_sel:WORD_1
	v_mov_b32_e32 v149, v3
	v_pk_fma_f32 v[32:33], v[0:1], s[4:5], v[32:33] op_sel_hi:[1,0,1]
	v_cvt_f32_f16_e32 v0, v210
	v_pk_fma_f32 v[34:35], v[202:203], s[4:5], v[34:35] op_sel_hi:[1,0,1]
	v_cvt_f32_f16_sdwa v1, v210 dst_sel:DWORD dst_unused:UNUSED_PAD src0_sel:WORD_1
	v_cvt_f32_f16_e32 v202, v211
	v_cvt_f32_f16_sdwa v203, v211 dst_sel:DWORD dst_unused:UNUSED_PAD src0_sel:WORD_1
	v_pk_fma_f32 v[104:105], v[0:1], s[4:5], v[104:105] op_sel_hi:[1,0,1]
	v_cvt_f32_f16_e32 v0, v212
	v_pk_fma_f32 v[106:107], v[202:203], s[4:5], v[106:107] op_sel_hi:[1,0,1]
	v_cvt_f32_f16_sdwa v1, v212 dst_sel:DWORD dst_unused:UNUSED_PAD src0_sel:WORD_1
	v_cvt_f32_f16_e32 v202, v213
	v_cvt_f32_f16_sdwa v203, v213 dst_sel:DWORD dst_unused:UNUSED_PAD src0_sel:WORD_1
	v_mov_b32_e32 v152, v3
	v_pk_fma_f32 v[84:85], v[0:1], s[4:5], v[84:85] op_sel_hi:[1,0,1]
	v_cvt_f32_f16_e32 v0, v214
	v_pk_fma_f32 v[86:87], v[202:203], s[4:5], v[86:87] op_sel_hi:[1,0,1]
	v_cvt_f32_f16_sdwa v1, v214 dst_sel:DWORD dst_unused:UNUSED_PAD src0_sel:WORD_1
	v_cvt_f32_f16_e32 v202, v215
	v_cvt_f32_f16_sdwa v203, v215 dst_sel:DWORD dst_unused:UNUSED_PAD src0_sel:WORD_1
	v_mov_b32_e32 v153, v3
	v_pk_fma_f32 v[48:49], v[0:1], s[4:5], v[48:49] op_sel_hi:[1,0,1]
	v_cvt_f32_f16_e32 v0, v216
	v_pk_fma_f32 v[50:51], v[202:203], s[4:5], v[50:51] op_sel_hi:[1,0,1]
	v_cvt_f32_f16_sdwa v1, v216 dst_sel:DWORD dst_unused:UNUSED_PAD src0_sel:WORD_1
	v_cvt_f32_f16_e32 v202, v217
	v_cvt_f32_f16_sdwa v203, v217 dst_sel:DWORD dst_unused:UNUSED_PAD src0_sel:WORD_1
	v_mov_b32_e32 v134, v3
	v_pk_fma_f32 v[28:29], v[0:1], s[4:5], v[28:29] op_sel_hi:[1,0,1]
	v_pk_fma_f32 v[30:31], v[202:203], s[4:5], v[30:31] op_sel_hi:[1,0,1]
	v_mov_b32_e32 v135, v3
	v_mov_b32_e32 v188, v3
	v_mov_b32_e32 v189, v3
	v_mov_b32_e32 v192, v3
	v_mov_b32_e32 v193, v3
	v_mov_b32_e32 v196, v3
	v_mov_b32_e32 v197, v3
	v_mov_b32_e32 v200, v3
	v_mov_b32_e32 v201, v3
	s_waitcnt vmcnt(0)
	s_nop 0
	v_cvt_f32_f16_e32 v0, v220
	v_cvt_f32_f16_sdwa v1, v220 dst_sel:DWORD dst_unused:UNUSED_PAD src0_sel:WORD_1
	v_cvt_f32_f16_e32 v134, v221
	v_cvt_f32_f16_sdwa v135, v221 dst_sel:DWORD dst_unused:UNUSED_PAD src0_sel:WORD_1
	v_mov_b32_e32 v148, v3
	v_pk_fma_f32 v[128:129], v[0:1], s[4:5], v[128:129] op_sel_hi:[1,0,1]
	v_cvt_f32_f16_e32 v0, v222
	v_cvt_f32_f16_sdwa v1, v222 dst_sel:DWORD dst_unused:UNUSED_PAD src0_sel:WORD_1
	v_pk_fma_f32 v[130:131], v[134:135], s[4:5], v[130:131] op_sel_hi:[1,0,1]
	v_cvt_f32_f16_e32 v134, v223
	v_cvt_f32_f16_sdwa v135, v223 dst_sel:DWORD dst_unused:UNUSED_PAD src0_sel:WORD_1
	v_pk_fma_f32 v[124:125], v[0:1], s[4:5], v[124:125] op_sel_hi:[1,0,1]
	v_cvt_f32_f16_e32 v0, v224
	v_cvt_f32_f16_sdwa v1, v224 dst_sel:DWORD dst_unused:UNUSED_PAD src0_sel:WORD_1
	v_pk_fma_f32 v[126:127], v[134:135], s[4:5], v[126:127] op_sel_hi:[1,0,1]
	v_cvt_f32_f16_e32 v134, v225
	v_cvt_f32_f16_sdwa v135, v225 dst_sel:DWORD dst_unused:UNUSED_PAD src0_sel:WORD_1
	v_pk_fma_f32 v[112:113], v[0:1], s[4:5], v[112:113] op_sel_hi:[1,0,1]
	v_cvt_f32_f16_e32 v0, v218
	v_cvt_f32_f16_sdwa v1, v218 dst_sel:DWORD dst_unused:UNUSED_PAD src0_sel:WORD_1
	v_cvt_f32_f16_e32 v218, v219
	v_cvt_f32_f16_sdwa v219, v219 dst_sel:DWORD dst_unused:UNUSED_PAD src0_sel:WORD_1
	v_pk_fma_f32 v[114:115], v[134:135], s[4:5], v[114:115] op_sel_hi:[1,0,1]
	v_pk_fma_f32 v[96:97], v[0:1], s[4:5], v[96:97] op_sel_hi:[1,0,1]
	v_cvt_f32_f16_e32 v0, v226
	v_pk_fma_f32 v[98:99], v[218:219], s[4:5], v[98:99] op_sel_hi:[1,0,1]
	v_cvt_f32_f16_sdwa v1, v226 dst_sel:DWORD dst_unused:UNUSED_PAD src0_sel:WORD_1
	v_cvt_f32_f16_e32 v218, v227
	v_cvt_f32_f16_sdwa v219, v227 dst_sel:DWORD dst_unused:UNUSED_PAD src0_sel:WORD_1
	v_pk_fma_f32 v[120:121], v[0:1], s[4:5], v[120:121] op_sel_hi:[1,0,1]
	v_cvt_f32_f16_e32 v0, v228
	v_pk_fma_f32 v[122:123], v[218:219], s[4:5], v[122:123] op_sel_hi:[1,0,1]
	v_cvt_f32_f16_sdwa v1, v228 dst_sel:DWORD dst_unused:UNUSED_PAD src0_sel:WORD_1
	v_cvt_f32_f16_e32 v218, v229
	v_cvt_f32_f16_sdwa v219, v229 dst_sel:DWORD dst_unused:UNUSED_PAD src0_sel:WORD_1
	v_mov_b32_e32 v149, v3
	v_pk_fma_f32 v[116:117], v[0:1], s[4:5], v[116:117] op_sel_hi:[1,0,1]
	v_cvt_f32_f16_e32 v0, v230
	v_pk_fma_f32 v[118:119], v[218:219], s[4:5], v[118:119] op_sel_hi:[1,0,1]
	v_cvt_f32_f16_sdwa v1, v230 dst_sel:DWORD dst_unused:UNUSED_PAD src0_sel:WORD_1
	v_cvt_f32_f16_e32 v218, v231
	v_cvt_f32_f16_sdwa v219, v231 dst_sel:DWORD dst_unused:UNUSED_PAD src0_sel:WORD_1
	v_mov_b32_e32 v138, v3
	v_pk_fma_f32 v[108:109], v[0:1], s[4:5], v[108:109] op_sel_hi:[1,0,1]
	v_cvt_f32_f16_e32 v0, v232
	v_pk_fma_f32 v[110:111], v[218:219], s[4:5], v[110:111] op_sel_hi:[1,0,1]
	v_cvt_f32_f16_sdwa v1, v232 dst_sel:DWORD dst_unused:UNUSED_PAD src0_sel:WORD_1
	v_cvt_f32_f16_e32 v218, v233
	v_cvt_f32_f16_sdwa v219, v233 dst_sel:DWORD dst_unused:UNUSED_PAD src0_sel:WORD_1
	v_mov_b32_e32 v139, v3
	v_pk_fma_f32 v[92:93], v[0:1], s[4:5], v[92:93] op_sel_hi:[1,0,1]
	v_add_u32_e32 v0, 0x28000, v2
	v_pk_fma_f32 v[94:95], v[218:219], s[4:5], v[94:95] op_sel_hi:[1,0,1]
	v_mov_b32_e32 v1, v3
	v_add_u32_e32 v2, 0x2c000, v2
	v_lshl_add_u64 v[132:133], v[0:1], 1, s[64:65]
	v_lshl_add_u64 v[134:135], v[2:3], 1, s[64:65]
	global_load_dwordx2 v[0:1], v[132:133], off
	global_load_dwordx2 v[146:147], v[132:133], off offset:32
	global_load_dwordx2 v[136:137], v[132:133], off offset:256
	s_nop 0
	global_load_dwordx2 v[132:133], v[132:133], off offset:288
	s_nop 0
	global_load_dwordx2 v[150:151], v[134:135], off
	global_load_dwordx2 v[186:187], v[134:135], off offset:32
	global_load_dwordx2 v[190:191], v[134:135], off offset:256
	global_load_dwordx2 v[194:195], v[134:135], off offset:288
	v_mov_b32_e32 v2, v3
	v_mov_b32_e32 v134, v3
	v_mov_b32_e32 v135, v3
	v_mov_b32_e32 v152, v3
	v_mov_b32_e32 v153, v3
	v_mov_b32_e32 v188, v3
	v_mov_b32_e32 v189, v3
	v_mov_b32_e32 v192, v3
	v_mov_b32_e32 v193, v3
	v_mov_b32_e32 v196, v3
	v_mov_b32_e32 v197, v3
	s_waitcnt vmcnt(7)
	v_mov_b64_e32 v[200:201], v[2:3]
	v_mov_b64_e32 v[198:199], v[0:1]
	s_waitcnt vmcnt(0)
	s_nop 0
	v_cvt_f32_f16_e32 v0, v198
	v_cvt_f32_f16_sdwa v1, v198 dst_sel:DWORD dst_unused:UNUSED_PAD src0_sel:WORD_1
	v_cvt_f32_f16_e32 v134, v199
	v_cvt_f32_f16_sdwa v135, v199 dst_sel:DWORD dst_unused:UNUSED_PAD src0_sel:WORD_1
	v_pk_fma_f32 v[80:81], v[0:1], s[4:5], v[80:81] op_sel_hi:[1,0,1]
	v_cvt_f32_f16_e32 v0, v146
	v_cvt_f32_f16_sdwa v1, v146 dst_sel:DWORD dst_unused:UNUSED_PAD src0_sel:WORD_1
	v_pk_fma_f32 v[82:83], v[134:135], s[4:5], v[82:83] op_sel_hi:[1,0,1]
	v_cvt_f32_f16_e32 v134, v147
	v_cvt_f32_f16_sdwa v135, v147 dst_sel:DWORD dst_unused:UNUSED_PAD src0_sel:WORD_1
	v_pk_fma_f32 v[76:77], v[0:1], s[4:5], v[76:77] op_sel_hi:[1,0,1]
	v_cvt_f32_f16_e32 v0, v136
	v_cvt_f32_f16_sdwa v1, v136 dst_sel:DWORD dst_unused:UNUSED_PAD src0_sel:WORD_1
	v_pk_fma_f32 v[78:79], v[134:135], s[4:5], v[78:79] op_sel_hi:[1,0,1]
	v_cvt_f32_f16_e32 v134, v137
	v_cvt_f32_f16_sdwa v135, v137 dst_sel:DWORD dst_unused:UNUSED_PAD src0_sel:WORD_1
	v_pk_fma_f32 v[64:65], v[0:1], s[4:5], v[64:65] op_sel_hi:[1,0,1]
	v_cvt_f32_f16_e32 v0, v132
	v_cvt_f32_f16_sdwa v1, v132 dst_sel:DWORD dst_unused:UNUSED_PAD src0_sel:WORD_1
	v_cvt_f32_f16_e32 v132, v133
	v_cvt_f32_f16_sdwa v133, v133 dst_sel:DWORD dst_unused:UNUSED_PAD src0_sel:WORD_1
	v_pk_fma_f32 v[66:67], v[134:135], s[4:5], v[66:67] op_sel_hi:[1,0,1]
	v_pk_fma_f32 v[60:61], v[0:1], s[4:5], v[60:61] op_sel_hi:[1,0,1]
	v_cvt_f32_f16_e32 v0, v150
	v_pk_fma_f32 v[62:63], v[132:133], s[4:5], v[62:63] op_sel_hi:[1,0,1]
	v_cvt_f32_f16_sdwa v1, v150 dst_sel:DWORD dst_unused:UNUSED_PAD src0_sel:WORD_1
	v_cvt_f32_f16_e32 v132, v151
	v_cvt_f32_f16_sdwa v133, v151 dst_sel:DWORD dst_unused:UNUSED_PAD src0_sel:WORD_1
	v_mov_b32_e32 v134, v24
	v_pk_fma_f32 v[72:73], v[0:1], s[4:5], v[72:73] op_sel_hi:[1,0,1]
	v_cvt_f32_f16_e32 v0, v186
	v_pk_fma_f32 v[74:75], v[132:133], s[4:5], v[74:75] op_sel_hi:[1,0,1]
	v_cvt_f32_f16_sdwa v1, v186 dst_sel:DWORD dst_unused:UNUSED_PAD src0_sel:WORD_1
	v_cvt_f32_f16_e32 v132, v187
	v_cvt_f32_f16_sdwa v133, v187 dst_sel:DWORD dst_unused:UNUSED_PAD src0_sel:WORD_1
	v_mov_b32_e32 v135, v27
	v_pk_fma_f32 v[68:69], v[0:1], s[4:5], v[68:69] op_sel_hi:[1,0,1]
	v_cvt_f32_f16_e32 v0, v190
	v_pk_fma_f32 v[70:71], v[132:133], s[4:5], v[70:71] op_sel_hi:[1,0,1]
	v_cvt_f32_f16_sdwa v1, v190 dst_sel:DWORD dst_unused:UNUSED_PAD src0_sel:WORD_1
	v_cvt_f32_f16_e32 v132, v191
	v_cvt_f32_f16_sdwa v133, v191 dst_sel:DWORD dst_unused:UNUSED_PAD src0_sel:WORD_1
	v_add_f32_e32 v137, v18, v19
	v_pk_fma_f32 v[56:57], v[0:1], s[4:5], v[56:57] op_sel_hi:[1,0,1]
	v_cvt_f32_f16_e32 v0, v194
	v_pk_fma_f32 v[58:59], v[132:133], s[4:5], v[58:59] op_sel_hi:[1,0,1]
	v_cvt_f32_f16_sdwa v1, v194 dst_sel:DWORD dst_unused:UNUSED_PAD src0_sel:WORD_1
	v_cvt_f32_f16_e32 v132, v195
	v_cvt_f32_f16_sdwa v133, v195 dst_sel:DWORD dst_unused:UNUSED_PAD src0_sel:WORD_1
	v_mov_b32_e32 v136, v9
	v_pk_fma_f32 v[44:45], v[0:1], s[4:5], v[44:45] op_sel_hi:[1,0,1]
	v_mov_b32_e32 v0, v37
	v_pk_fma_f32 v[46:47], v[132:133], s[4:5], v[46:47] op_sel_hi:[1,0,1]
	v_mov_b32_e32 v1, v38
	v_mov_b32_e32 v132, v36
	v_mov_b32_e32 v133, v39
	v_pk_add_f32 v[0:1], v[0:1], v[132:133]
	v_mov_b32_e32 v132, v25
	v_mov_b32_e32 v133, v26
	v_pk_add_f32 v[132:133], v[132:133], v[134:135]
	v_add_f32_e32 v0, v0, v1
	v_pk_add_f32 v[132:133], v[132:133], v[132:133] op_sel_hi:[0,1]
	v_add_f32_e32 v1, 0, v0
	v_add_f32_e32 v135, v16, v17
	v_mov_b32_e32 v134, v8
	v_mov_b32_e32 v132, v10
	v_mov_b32_e32 v0, v11
	v_pk_add_f32 v[134:135], v[134:135], v[136:137]
	v_pk_add_f32 v[0:1], v[132:133], v[0:1]
	s_lshl_b32 s4, s8, 3
	v_pk_add_f32 v[0:1], v[134:135], v[0:1]
	s_add_i32 s7, s4, 0
	v_add_f32_e32 v0, v0, v1
	v_mov_b32_e32 v1, v0
	s_nop 1
	v_permlane16_swap_b32 v0, v1
	s_waitcnt lgkmcnt(0)
	v_add_f32_e32 v0, v0, v1
	v_mov_b32_e32 v1, v0
	s_nop 1
	v_permlane32_swap_b32 v0, v1
	s_waitcnt lgkmcnt(0)
	v_add_f32_e32 v0, v0, v1
	v_fmamk_f32 v2, v0, 0xbc800000, v39
	v_fmamk_f32 v133, v0, 0xbc800000, v37
	v_fmamk_f32 v1, v0, 0xbc800000, v38
	v_fmamk_f32 v132, v0, 0xbc800000, v36
	v_mul_f32_e32 v133, v133, v133
	v_mul_f32_e32 v2, v2, v2
	v_fmac_f32_e32 v133, v132, v132
	v_fmac_f32_e32 v2, v1, v1
	v_fmamk_f32 v132, v0, 0xbc800000, v27
	v_fmamk_f32 v134, v0, 0xbc800000, v25
	v_add_f32_e32 v1, v133, v2
	v_fmamk_f32 v2, v0, 0xbc800000, v26
	v_fmamk_f32 v133, v0, 0xbc800000, v24
	v_mul_f32_e32 v134, v134, v134
	v_mul_f32_e32 v132, v132, v132
	v_fmac_f32_e32 v134, v133, v133
	v_fmac_f32_e32 v132, v2, v2
	v_add_f32_e32 v2, v134, v132
	v_fmamk_f32 v132, v0, 0xbc800000, v19
	v_fmamk_f32 v134, v0, 0xbc800000, v17
	v_add_f32_e32 v1, v1, v2
	v_fmamk_f32 v2, v0, 0xbc800000, v18
	v_fmamk_f32 v133, v0, 0xbc800000, v16
	v_mul_f32_e32 v134, v134, v134
	v_mul_f32_e32 v132, v132, v132
	v_fmac_f32_e32 v134, v133, v133
	v_fmac_f32_e32 v132, v2, v2
	v_add_f32_e32 v2, v134, v132
	v_fmamk_f32 v132, v0, 0xbc800000, v11
	v_fmamk_f32 v134, v0, 0xbc800000, v9
	v_add_f32_e32 v1, v2, v1
	v_fmamk_f32 v2, v0, 0xbc800000, v10
	v_fmamk_f32 v133, v0, 0xbc800000, v8
	v_mul_f32_e32 v134, v134, v134
	v_mul_f32_e32 v132, v132, v132
	v_fmac_f32_e32 v134, v133, v133
	v_fmac_f32_e32 v132, v2, v2
	v_add_f32_e32 v2, v134, v132
	v_add_f32_e32 v1, v2, v1
	v_mov_b32_e32 v2, v1
	s_nop 1
	v_permlane16_swap_b32 v1, v2
	s_waitcnt lgkmcnt(0)
	v_add_f32_e32 v1, v1, v2
	v_mov_b32_e32 v2, v1
	s_nop 1
	v_permlane32_swap_b32 v1, v2
	s_and_saveexec_b64 s[4:5], vcc
	s_cbranch_execz .LBB0_1212
	s_lshl_b32 s8, s0, 11
	s_add_i32 s8, s7, s8
	v_mul_f32_e32 v0, 0x3c800000, v0
	s_waitcnt lgkmcnt(0)
	v_add_f32_e32 v1, v1, v2
	v_lshl_add_u32 v2, v144, 5, s8
	ds_write_b64 v2, v[0:1]
